# LN1 stores row statistics instead of the normalized f32 stream; w_down epilogue recomputes it from the pre-LN tensor (same f32 ops); on top of prologue overlaps, phase-4 rebalance, NA bias fix, MLA in
# speedup vs baseline: 1.0091x; 1.0030x over previous
; __device__ __forceinline__ void phase_ln(const float* z, float* xo, const float* __restrict__ g, const float* __restrict__ b, const float* __restrict__ sc, const float* __restrict__ sh, bf16_t* __restrict__ u) {
;     ...
;     for (int r = blockIdx.x * 8 + wave; r < S; r += 2 * stride) {
;         const bool hasB = r + stride < S; const int rr[2] = {r, hasB ? r + stride : r};
;         f32x4 v[2][8]; float s[2] = {0.f, 0.f};
; #pragma unroll
;         for (int k = 0; k < 2; ++k) { const float* zr = z + (size_t)rr[k] * DM;
; #pragma unroll
;             for (int j = 0; j < 8; ++j) v[k][j] = *(const f32x4*)(zr + j * 256 + 4 * lane); }
; #pragma unroll
;         for (int k = 0; k < 2; ++k)
; #pragma unroll
;             for (int j = 0; j < 8; ++j) s[k] += (v[k][j][0] + v[k][j][1]) + (v[k][j][2] + v[k][j][3]);
;         float mean[2], rstd[2];
; #pragma unroll
;         for (int k = 0; k < 2; ++k) { mean[k] = wave_sum(s[k]) * (1.0f / DM); float q = 0.f;
; #pragma unroll
;             for (int j = 0; j < 8; ++j) { const f32x4 d = v[k][j] - mean[k]; q += (d[0] * d[0] + d[1] * d[1]) + (d[2] * d[2] + d[3] * d[3]); }
.LBB0_1073:
	v_lshl_add_u64 v[172:173], s[2:3], 0, v[168:169]
	v_add_co_u32_e32 v182, vcc, 0xb828000, v172
	v_add_u32_e32 v0, s16, v80
	s_nop 0
	v_addc_co_u32_e32 v183, vcc, 0, v173, vcc
	flat_load_dwordx4 v[74:77], v[182:183]
	flat_load_dwordx4 v[66:69], v[182:183] offset:1024
	flat_load_dwordx4 v[58:61], v[182:183] offset:2048
	flat_load_dwordx4 v[50:53], v[182:183] offset:3072
	v_add_co_u32_e32 v14, vcc, 0xb829000, v172
	v_cmp_gt_i32_e64 s[4:5], s17, v0
	s_nop 0
	v_addc_co_u32_e32 v15, vcc, 0, v173, vcc
	flat_load_dwordx4 v[42:45], v[14:15]
	flat_load_dwordx4 v[34:37], v[14:15] offset:1024
	flat_load_dwordx4 v[26:29], v[14:15] offset:2048
	flat_load_dwordx4 v[18:21], v[14:15] offset:3072
	v_cndmask_b32_e64 v78, v80, v0, s[4:5]
	v_ashrrev_i32_e32 v79, 31, v78
	v_lshlrev_b64 v[170:171], 13, v[78:79]
	v_lshl_add_u64 v[198:199], v[126:127], 0, v[170:171]
	flat_load_dwordx4 v[70:73], v[198:199]
	flat_load_dwordx4 v[62:65], v[198:199] offset:1024
	flat_load_dwordx4 v[54:57], v[198:199] offset:2048
	flat_load_dwordx4 v[46:49], v[198:199] offset:3072
	v_add_co_u32_e32 v14, vcc, s18, v198
	v_lshl_add_u64 v[184:185], s[2:3], 0, v[166:167]
	s_nop 0
	v_addc_co_u32_e32 v15, vcc, 0, v199, vcc
	flat_load_dwordx4 v[38:41], v[14:15]
	flat_load_dwordx4 v[30:33], v[14:15] offset:1024
	flat_load_dwordx4 v[22:25], v[14:15] offset:2048
	s_nop 0
	flat_load_dwordx4 v[14:17], v[14:15] offset:3072
	s_waitcnt vmcnt(0) lgkmcnt(0)
	v_add_f32_e32 v0, v74, v75
	v_add_f32_e32 v81, v76, v77
	v_add_f32_e32 v0, v0, v81
	v_add_f32_e32 v81, v66, v67
	v_add_f32_e32 v174, v68, v69
	v_add_f32_e32 v0, 0, v0
	v_add_f32_e32 v81, v81, v174
	v_add_f32_e32 v0, v0, v81
	v_add_f32_e32 v81, v58, v59
	v_add_f32_e32 v174, v60, v61
	v_add_f32_e32 v81, v81, v174
	v_add_f32_e32 v0, v0, v81
	v_add_f32_e32 v81, v50, v51
	v_add_f32_e32 v174, v52, v53
	v_add_f32_e32 v81, v81, v174
	v_add_f32_e32 v0, v0, v81
	v_add_f32_e32 v81, v42, v43
	v_add_f32_e32 v174, v44, v45
	v_add_f32_e32 v81, v81, v174
	v_add_f32_e32 v0, v0, v81
	v_add_f32_e32 v81, v34, v35
	v_add_f32_e32 v174, v36, v37
	v_add_f32_e32 v81, v81, v174
	v_add_f32_e32 v0, v0, v81
	v_add_f32_e32 v81, v26, v27
	v_add_f32_e32 v174, v28, v29
	v_add_f32_e32 v81, v81, v174
	v_add_f32_e32 v0, v0, v81
	v_add_f32_e32 v81, v18, v19
	v_add_f32_e32 v174, v20, v21
	v_add_f32_e32 v81, v81, v174
	v_add_f32_e32 v0, v0, v81
	v_add_f32_e32 v81, v70, v71
	v_add_f32_e32 v174, v72, v73
	v_add_f32_e32 v81, v81, v174
	v_add_f32_e32 v174, v62, v63
	v_add_f32_e32 v175, v64, v65
	v_add_f32_e32 v81, 0, v81
	v_add_f32_e32 v174, v174, v175
	v_add_f32_e32 v81, v81, v174
	v_add_f32_e32 v174, v54, v55
	v_add_f32_e32 v175, v56, v57
	v_add_f32_e32 v174, v174, v175
	v_add_f32_e32 v81, v81, v174
	v_add_f32_e32 v174, v46, v47
	v_add_f32_e32 v175, v48, v49
	v_add_f32_e32 v174, v174, v175
	v_add_f32_e32 v81, v81, v174
	v_add_f32_e32 v174, v38, v39
	v_add_f32_e32 v175, v40, v41
	v_add_f32_e32 v174, v174, v175
	v_add_f32_e32 v81, v81, v174
	v_add_f32_e32 v174, v30, v31
	v_add_f32_e32 v175, v32, v33
	v_add_f32_e32 v174, v174, v175
	v_add_f32_e32 v81, v81, v174
	v_add_f32_e32 v174, v22, v23
	v_add_f32_e32 v175, v24, v25
	v_add_f32_dpp v0, v0, v0 quad_perm:[1,0,3,2] row_mask:0xf bank_mask:0xf bound_ctrl:1
	v_add_f32_e32 v174, v174, v175
	v_add_f32_e32 v81, v81, v174
	v_add_f32_dpp v0, v0, v0 quad_perm:[2,3,0,1] row_mask:0xf bank_mask:0xf bound_ctrl:1
	v_add_f32_e32 v174, v14, v15
	v_add_f32_e32 v175, v16, v17
	v_add_f32_dpp v0, v0, v0 row_half_mirror row_mask:0xf bank_mask:0xf bound_ctrl:1
	v_add_f32_e32 v174, v174, v175
	v_add_f32_e32 v81, v81, v174
	v_add_f32_dpp v0, v0, v0 row_mirror row_mask:0xf bank_mask:0xf bound_ctrl:1
	v_mov_b32_e32 v174, v0
	s_nop 1
	v_permlane16_swap_b32_e32 v0, v174
	v_add_f32_e32 v0, v0, v174
	v_mov_b32_e32 v174, v0
	s_nop 1
	v_permlane32_swap_b32_e32 v0, v174
	v_add_f32_e32 v0, v0, v174
	v_mov_b32_e32 v240, v0
	v_fmamk_f32 v77, v0, 0xba000000, v77
	v_fmac_f32_e32 v75, 0xba000000, v0
	v_fmamk_f32 v203, v0, 0xba000000, v69
	v_fmamk_f32 v67, v0, 0xba000000, v67
	v_fmamk_f32 v76, v0, 0xba000000, v76
	v_fmamk_f32 v74, v0, 0xba000000, v74
	v_mul_f32_e32 v174, v75, v75
	v_mul_f32_e32 v175, v77, v77
	v_fmamk_f32 v202, v0, 0xba000000, v68
	v_fmac_f32_e32 v66, 0xba000000, v0
	v_mul_f32_e32 v68, v67, v67
	v_mul_f32_e32 v69, v203, v203
	v_fmamk_f32 v201, v0, 0xba000000, v61
	v_fmamk_f32 v59, v0, 0xba000000, v59
	v_fmac_f32_e32 v174, v74, v74
	v_fmac_f32_e32 v175, v76, v76
	v_fmac_f32_e32 v68, v66, v66
	v_fmac_f32_e32 v69, v202, v202
	v_fmamk_f32 v200, v0, 0xba000000, v60
	v_fmac_f32_e32 v58, 0xba000000, v0
	v_mul_f32_e32 v60, v59, v59
	v_mul_f32_e32 v61, v201, v201
	v_fmamk_f32 v197, v0, 0xba000000, v53
	v_fmamk_f32 v51, v0, 0xba000000, v51
	v_add_f32_e32 v174, v174, v175
	v_add_f32_e32 v68, v68, v69
	v_fmac_f32_e32 v60, v58, v58
	v_fmac_f32_e32 v61, v200, v200
	v_fmamk_f32 v196, v0, 0xba000000, v52
	v_fmac_f32_e32 v50, 0xba000000, v0
	v_mul_f32_e32 v52, v51, v51
	v_mul_f32_e32 v53, v197, v197
	v_fmamk_f32 v195, v0, 0xba000000, v45
	v_fmamk_f32 v43, v0, 0xba000000, v43
	v_add_f32_e32 v68, v174, v68
	v_add_f32_e32 v60, v60, v61
	v_fmac_f32_e32 v52, v50, v50
	v_fmac_f32_e32 v53, v196, v196
	v_fmamk_f32 v194, v0, 0xba000000, v44
	v_fmac_f32_e32 v42, 0xba000000, v0
	v_mul_f32_e32 v44, v43, v43
	v_mul_f32_e32 v45, v195, v195
	v_fmamk_f32 v181, v0, 0xba000000, v37
	v_fmamk_f32 v35, v0, 0xba000000, v35
	v_add_f32_e32 v60, v60, v68
	v_add_f32_e32 v52, v52, v53
	v_fmac_f32_e32 v44, v42, v42
	v_fmac_f32_e32 v45, v194, v194
	v_fmamk_f32 v180, v0, 0xba000000, v36
	v_fmac_f32_e32 v34, 0xba000000, v0
	v_mul_f32_e32 v36, v35, v35
	v_mul_f32_e32 v37, v181, v181
; __device__ __forceinline__ void phase_ln(const float* z, float* xo, const float* __restrict__ g, const float* __restrict__ b, const float* __restrict__ sc, const float* __restrict__ sh, bf16_t* __restrict__ u) {
;     ...
;         for (int k = 0; k < 2; ++k) { mean[k] = wave_sum(s[k]) * (1.0f / DM); float q = 0.f;
; #pragma unroll
;             for (int j = 0; j < 8; ++j) { const f32x4 d = v[k][j] - mean[k]; q += (d[0] * d[0] + d[1] * d[1]) + (d[2] * d[2] + d[3] * d[3]); }
;             rstd[k] = 1.0f / sqrtf(wave_sum(q) * (1.0f / DM) + 1e-5f); }
	v_fmamk_f32 v179, v0, 0xba000000, v29
	v_fmamk_f32 v27, v0, 0xba000000, v27
	v_add_f32_e32 v52, v52, v60
	v_add_f32_e32 v44, v44, v45
	v_fmac_f32_e32 v36, v34, v34
	v_fmac_f32_e32 v37, v180, v180
	v_fmamk_f32 v178, v0, 0xba000000, v28
	v_fmac_f32_e32 v26, 0xba000000, v0
	v_mul_f32_e32 v28, v27, v27
	v_mul_f32_e32 v29, v179, v179
	v_fmamk_f32 v175, v0, 0xba000000, v21
	v_fmamk_f32 v19, v0, 0xba000000, v19
	v_add_f32_e32 v44, v44, v52
	v_add_f32_e32 v36, v36, v37
	v_fmac_f32_e32 v28, v26, v26
	v_fmac_f32_e32 v29, v178, v178
	v_fmamk_f32 v174, v0, 0xba000000, v20
	v_fmac_f32_e32 v18, 0xba000000, v0
	v_mul_f32_e32 v0, v19, v19
	v_mul_f32_e32 v20, v175, v175
	v_add_f32_e32 v36, v36, v44
	v_add_f32_e32 v28, v28, v29
	v_fmac_f32_e32 v0, v18, v18
	v_fmac_f32_e32 v20, v174, v174
	v_add_f32_e32 v28, v28, v36
	v_add_f32_e32 v0, v0, v20
	v_add_f32_e32 v0, v0, v28
	s_nop 1
	v_add_f32_dpp v0, v0, v0 quad_perm:[1,0,3,2] row_mask:0xf bank_mask:0xf bound_ctrl:1
	s_nop 1
	v_add_f32_dpp v0, v0, v0 quad_perm:[2,3,0,1] row_mask:0xf bank_mask:0xf bound_ctrl:1
	s_nop 1
	v_add_f32_dpp v0, v0, v0 row_half_mirror row_mask:0xf bank_mask:0xf bound_ctrl:1
	s_nop 1
	v_add_f32_dpp v0, v0, v0 row_mirror row_mask:0xf bank_mask:0xf bound_ctrl:1
	v_mov_b32_e32 v20, v0
	s_nop 1
	v_permlane16_swap_b32_e32 v0, v20
	v_add_f32_e32 v0, v0, v20
	v_mov_b32_e32 v20, v0
	s_nop 1
	v_permlane32_swap_b32_e32 v0, v20
	v_add_f32_e32 v0, v0, v20
	v_fmamk_f32 v0, v0, 0x3a000000, v220
	v_cmp_gt_f32_e32 vcc, s77, v0
	v_mul_f32_e32 v20, 0x4f800000, v0
	s_nop 0
	v_cndmask_b32_e32 v0, v0, v20, vcc
	v_sqrt_f32_e32 v20, v0
	s_nop 0
	v_add_u32_e32 v21, -1, v20
	v_fma_f32 v28, -v21, v20, v0
	v_cmp_ge_f32_e64 s[0:1], 0, v28
	v_add_u32_e32 v28, 1, v20
	s_nop 0
	v_cndmask_b32_e64 v21, v20, v21, s[0:1]
	v_fma_f32 v20, -v28, v20, v0
	v_cmp_lt_f32_e64 s[0:1], 0, v20
	s_nop 1
	v_cndmask_b32_e64 v20, v21, v28, s[0:1]
	v_mul_f32_e32 v21, 0x37800000, v20
	v_cndmask_b32_e32 v20, v20, v21, vcc
	v_cmp_class_f32_e32 vcc, v0, v219
	s_nop 1
	v_cndmask_b32_e32 v0, v20, v0, vcc
	v_div_scale_f32 v20, s[0:1], v0, v0, 1.0
	v_rcp_f32_e32 v21, v20
	s_nop 0
	v_fma_f32 v28, -v20, v21, 1.0
	v_fmac_f32_e32 v21, v28, v21
	v_div_scale_f32 v28, vcc, 1.0, v0, 1.0
	v_mul_f32_e32 v29, v28, v21
	v_fma_f32 v36, -v20, v29, v28
	v_fmac_f32_e32 v29, v36, v21
	v_fma_f32 v20, -v20, v29, v28
	v_div_fmas_f32 v20, v20, v21, v29
	v_div_fixup_f32 v176, v20, v0, 1.0
	v_add_f32_dpp v0, v81, v81 quad_perm:[1,0,3,2] row_mask:0xf bank_mask:0xf bound_ctrl:1
	s_nop 1
	v_add_f32_dpp v0, v0, v0 quad_perm:[2,3,0,1] row_mask:0xf bank_mask:0xf bound_ctrl:1
	s_nop 1
	v_add_f32_dpp v0, v0, v0 row_half_mirror row_mask:0xf bank_mask:0xf bound_ctrl:1
	s_nop 1
	v_add_f32_dpp v0, v0, v0 row_mirror row_mask:0xf bank_mask:0xf bound_ctrl:1
	v_mov_b32_e32 v20, v0
	s_nop 1
	v_permlane16_swap_b32_e32 v0, v20
	v_add_f32_e32 v0, v0, v20
	v_mov_b32_e32 v20, v0
	s_nop 1
	v_permlane32_swap_b32_e32 v0, v20
	v_add_f32_e32 v0, v0, v20
	v_mov_b32_e32 v241, v0
	v_fmamk_f32 v69, v0, 0xba000000, v73
	v_fmamk_f32 v71, v0, 0xba000000, v71
	v_fmamk_f32 v68, v0, 0xba000000, v72
	v_fmac_f32_e32 v70, 0xba000000, v0
	v_mul_f32_e32 v20, v71, v71
	v_mul_f32_e32 v21, v69, v69
	v_fmac_f32_e32 v20, v70, v70
	v_fmac_f32_e32 v21, v68, v68
	v_fmamk_f32 v61, v0, 0xba000000, v65
	v_fmamk_f32 v63, v0, 0xba000000, v63
	v_add_f32_e32 v20, v20, v21
	v_fmamk_f32 v60, v0, 0xba000000, v64
	v_fmac_f32_e32 v62, 0xba000000, v0
	v_mul_f32_e32 v21, v63, v63
	v_mul_f32_e32 v28, v61, v61
	v_fmac_f32_e32 v21, v62, v62
	v_fmac_f32_e32 v28, v60, v60
	v_add_f32_e32 v21, v21, v28
	v_fmamk_f32 v53, v0, 0xba000000, v57
	v_fmamk_f32 v55, v0, 0xba000000, v55
	v_add_f32_e32 v20, v20, v21
	v_fmamk_f32 v52, v0, 0xba000000, v56
	v_fmac_f32_e32 v54, 0xba000000, v0
	v_mul_f32_e32 v21, v55, v55
	v_mul_f32_e32 v28, v53, v53
	v_fmac_f32_e32 v21, v54, v54
	v_fmac_f32_e32 v28, v52, v52
	v_add_f32_e32 v21, v21, v28
	v_fmamk_f32 v45, v0, 0xba000000, v49
	v_fmamk_f32 v47, v0, 0xba000000, v47
	v_add_f32_e32 v20, v21, v20
	v_fmamk_f32 v44, v0, 0xba000000, v48
	v_fmac_f32_e32 v46, 0xba000000, v0
	v_mul_f32_e32 v21, v47, v47
	v_mul_f32_e32 v28, v45, v45
	v_fmac_f32_e32 v21, v46, v46
	v_fmac_f32_e32 v28, v44, v44
	v_add_f32_e32 v21, v21, v28
	v_fmamk_f32 v37, v0, 0xba000000, v41
	v_fmamk_f32 v39, v0, 0xba000000, v39
	v_add_f32_e32 v20, v21, v20
	v_fmamk_f32 v36, v0, 0xba000000, v40
	v_fmac_f32_e32 v38, 0xba000000, v0
	v_mul_f32_e32 v21, v39, v39
	v_mul_f32_e32 v28, v37, v37
	v_fmac_f32_e32 v21, v38, v38
	v_fmac_f32_e32 v28, v36, v36
	v_add_f32_e32 v21, v21, v28
	v_fmamk_f32 v29, v0, 0xba000000, v33
	v_fmamk_f32 v31, v0, 0xba000000, v31
	v_add_f32_e32 v20, v21, v20
	v_fmamk_f32 v28, v0, 0xba000000, v32
	v_fmac_f32_e32 v30, 0xba000000, v0
	v_mul_f32_e32 v21, v31, v31
	v_mul_f32_e32 v32, v29, v29
	v_fmac_f32_e32 v21, v30, v30
	v_fmac_f32_e32 v32, v28, v28
	v_add_f32_e32 v21, v21, v32
	v_add_f32_e32 v32, v21, v20
	v_fmamk_f32 v21, v0, 0xba000000, v25
	v_fmamk_f32 v23, v0, 0xba000000, v23
	v_fmamk_f32 v20, v0, 0xba000000, v24
	v_fmac_f32_e32 v22, 0xba000000, v0
	v_mul_f32_e32 v24, v23, v23
	v_mul_f32_e32 v25, v21, v21
	v_fmac_f32_e32 v24, v22, v22
	v_fmac_f32_e32 v25, v20, v20
	v_fmamk_f32 v17, v0, 0xba000000, v17
	v_fmamk_f32 v15, v0, 0xba000000, v15
	v_add_f32_e32 v24, v24, v25
	v_fmamk_f32 v16, v0, 0xba000000, v16
	v_fmac_f32_e32 v14, 0xba000000, v0
	v_mul_f32_e32 v0, v15, v15
	v_mul_f32_e32 v25, v17, v17
	v_fmac_f32_e32 v0, v14, v14
	v_fmac_f32_e32 v25, v16, v16
	v_add_f32_e32 v24, v24, v32
	v_add_f32_e32 v0, v0, v25
	v_add_f32_e32 v0, v0, v24
	s_nop 1
	v_add_f32_dpp v0, v0, v0 quad_perm:[1,0,3,2] row_mask:0xf bank_mask:0xf bound_ctrl:1
; __device__ __forceinline__ unsigned cvt_pk_bf16(float lo, float hi) { unsigned r; asm volatile("v_cvt_pk_bf16_f32 %0, %1, %2" : "=v"(r) : "v"(lo), "v"(hi)); return r; }
; __device__ __forceinline__ void phase_ln(const float* z, float* xo, const float* __restrict__ g, const float* __restrict__ b, const float* __restrict__ sc, const float* __restrict__ sh, bf16_t* __restrict__ u) {
;     ...
;         for (int k = 0; k < 2; ++k) { mean[k] = wave_sum(s[k]) * (1.0f / DM); float q = 0.f;
; #pragma unroll
;             for (int j = 0; j < 8; ++j) { const f32x4 d = v[k][j] - mean[k]; q += (d[0] * d[0] + d[1] * d[1]) + (d[2] * d[2] + d[3] * d[3]); }
;             rstd[k] = 1.0f / sqrtf(wave_sum(q) * (1.0f / DM) + 1e-5f); }
; #pragma unroll
;         for (int j = 0; j < 8; ++j) { const int col = j * 256 + 4 * lane;
;             const f32x4 gg = *(const f32x4*)(g + col), bb = *(const f32x4*)(b + col);
;             f32x4 s1 = {0.f, 0.f, 0.f, 0.f}, h1 = {0.f, 0.f, 0.f, 0.f};
;             if (u) { s1 = *(const f32x4*)(sc + col) + 1.0f; h1 = *(const f32x4*)(sh + col); }
; #pragma unroll
;             for (int k = 0; k < 2; ++k) { if (k == 1 && !hasB) continue;
;                 const f32x4 o = (v[k][j] - mean[k]) * rstd[k] * gg + bb;
;                 *(f32x4*)(xo + (size_t)rr[k] * DM + col) = o;
;                 if (u) { const f32x4 m = o * s1 + h1; u32x2 w; w.x = cvt_pk_bf16(m[0], m[1]); w.y = cvt_pk_bf16(m[2], m[3]); *(u32x2*)(u + (size_t)rr[k] * DM + col) = w; } } }
	s_nop 1
	v_add_f32_dpp v0, v0, v0 quad_perm:[2,3,0,1] row_mask:0xf bank_mask:0xf bound_ctrl:1
	s_nop 1
	v_add_f32_dpp v0, v0, v0 row_half_mirror row_mask:0xf bank_mask:0xf bound_ctrl:1
	s_nop 1
	v_add_f32_dpp v0, v0, v0 row_mirror row_mask:0xf bank_mask:0xf bound_ctrl:1
	v_mov_b32_e32 v24, v0
	s_nop 1
	v_permlane16_swap_b32_e32 v0, v24
	v_add_f32_e32 v0, v0, v24
	v_mov_b32_e32 v24, v0
	s_nop 1
	v_permlane32_swap_b32_e32 v0, v24
	v_add_f32_e32 v0, v0, v24
	v_fmamk_f32 v0, v0, 0x3a000000, v220
	v_cmp_gt_f32_e32 vcc, s77, v0
	v_mul_f32_e32 v24, 0x4f800000, v0
	s_nop 0
	v_cndmask_b32_e32 v0, v0, v24, vcc
	v_sqrt_f32_e32 v24, v0
	s_nop 0
	v_add_u32_e32 v25, -1, v24
	v_fma_f32 v32, -v25, v24, v0
	v_cmp_ge_f32_e64 s[0:1], 0, v32
	v_add_u32_e32 v32, 1, v24
	s_nop 0
	v_cndmask_b32_e64 v25, v24, v25, s[0:1]
	v_fma_f32 v24, -v32, v24, v0
	v_cmp_lt_f32_e64 s[0:1], 0, v24
	s_nop 1
	v_cndmask_b32_e64 v24, v25, v32, s[0:1]
	v_mul_f32_e32 v25, 0x37800000, v24
	v_cndmask_b32_e32 v24, v24, v25, vcc
	v_cmp_class_f32_e32 vcc, v0, v219
	s_nop 1
	v_cndmask_b32_e32 v0, v24, v0, vcc
	v_div_scale_f32 v24, s[0:1], v0, v0, 1.0
	v_rcp_f32_e32 v25, v24
	s_nop 0
	v_fma_f32 v32, -v24, v25, 1.0
	v_fmac_f32_e32 v25, v32, v25
	v_div_scale_f32 v32, vcc, 1.0, v0, 1.0
	v_mul_f32_e32 v33, v32, v25
	v_fma_f32 v40, -v24, v33, v32
	v_fmac_f32_e32 v33, v40, v25
	v_fma_f32 v24, -v24, v33, v32
	v_div_fmas_f32 v24, v24, v25, v33
	v_div_fixup_f32 v0, v24, v0, 1.0
	s_add_u32 s0, s2, 0xb818000
	s_addc_u32 s1, s3, 0
	v_lshlrev_b32_e32 v242, 3, v80
	v_lshlrev_b32_e32 v243, 3, v78
	v_mov_b32_e32 v244, v240
	v_mov_b32_e32 v245, v176
	v_mov_b32_e32 v246, v241
	v_mov_b32_e32 v247, v0
	global_store_dwordx2 v242, v[244:245], s[0:1]
	global_store_dwordx2 v243, v[246:247], s[0:1]
	v_pk_mul_f32 v[24:25], v[74:75], v[176:177] op_sel_hi:[1,0]
	v_pk_mul_f32 v[32:33], v[76:77], v[176:177] op_sel_hi:[1,0]
	v_pk_fma_f32 v[72:73], v[10:11], v[24:25], v[2:3]
	v_pk_fma_f32 v[74:75], v[12:13], v[32:33], v[4:5]
	v_pk_fma_f32 v[32:33], v[72:73], v[156:157], v[6:7]
	v_pk_fma_f32 v[24:25], v[74:75], v[154:155], v[8:9]
	v_cvt_pk_bf16_f32 v32, v32, v33
	v_cvt_pk_bf16_f32 v33, v24, v25
	v_add_co_u32_e32 v24, vcc, 0xf828000, v184
	v_lshlrev_b64 v[182:183], 12, v[78:79]
	s_nop 0
	v_addc_co_u32_e32 v25, vcc, 0, v185, vcc
	flat_store_dwordx2 v[24:25], v[32:33]
	s_and_saveexec_b64 s[0:1], s[4:5]
	s_cbranch_execz .LBB0_1075
	v_pk_mul_f32 v[24:25], v[68:69], v[0:1] op_sel_hi:[1,0]
	v_pk_mul_f32 v[32:33], v[70:71], v[0:1] op_sel_hi:[1,0]
	v_pk_fma_f32 v[70:71], v[12:13], v[24:25], v[4:5]
	v_pk_fma_f32 v[68:69], v[10:11], v[32:33], v[2:3]
	v_pk_fma_f32 v[24:25], v[154:155], v[70:71], v[8:9]
	v_pk_fma_f32 v[32:33], v[156:157], v[68:69], v[6:7]
	v_cvt_pk_bf16_f32 v32, v32, v33
	v_cvt_pk_bf16_f32 v33, v24, v25
	v_lshl_add_u64 v[24:25], v[140:141], 0, v[182:183]
	flat_store_dwordx2 v[24:25], v[32:33]
.LBB0_1075:
	s_or_b64 exec, exec, s[0:1]
	flat_load_dwordx4 v[68:71], v[82:83] offset:1024
	flat_load_dwordx4 v[72:75], v[84:85] offset:1024
	flat_load_dwordx4 v[76:79], v[144:145]
	v_mov_b32_e32 v177, v176
	v_mov_b32_e32 v24, v176
	v_mov_b32_e32 v25, v176
	s_mov_b64 s[0:1], 0xb828400
	v_pk_mul_f32 v[56:57], v[202:203], v[24:25]
	v_pk_mul_f32 v[64:65], v[66:67], v[176:177]
	v_lshl_add_u64 v[48:49], v[172:173], 0, s[0:1]
	s_waitcnt vmcnt(0) lgkmcnt(0)
	v_pk_fma_f32 v[66:67], v[56:57], v[70:71], v[74:75]
	v_pk_add_f32 v[32:33], v[78:79], 1.0 op_sel_hi:[1,0]
	v_pk_add_f32 v[40:41], v[76:77], 1.0 op_sel_hi:[1,0]
	flat_load_dwordx4 v[76:79], v[142:143]
	v_pk_fma_f32 v[64:65], v[64:65], v[68:69], v[72:73]
	s_waitcnt vmcnt(0) lgkmcnt(0)
	v_pk_fma_f32 v[48:49], v[66:67], v[32:33], v[78:79]
	v_pk_fma_f32 v[56:57], v[64:65], v[40:41], v[76:77]
	s_nop 0
	v_cvt_pk_bf16_f32 v56, v56, v57
	v_cvt_pk_bf16_f32 v57, v48, v49
	v_add_co_u32_e32 v48, vcc, 0xf828000, v184
	s_nop 1
	v_addc_co_u32_e32 v49, vcc, 0, v185, vcc
	flat_store_dwordx2 v[48:49], v[56:57] offset:512
	s_and_saveexec_b64 s[0:1], s[4:5]
	s_cbranch_execz .LBB0_1077
	v_pk_mul_f32 v[48:49], v[60:61], v[0:1] op_sel_hi:[1,0]
	v_pk_mul_f32 v[56:57], v[62:63], v[0:1] op_sel_hi:[1,0]
	v_pk_fma_f32 v[62:63], v[48:49], v[70:71], v[74:75]
	v_pk_fma_f32 v[60:61], v[56:57], v[68:69], v[72:73]
	v_lshl_add_u64 v[48:49], v[146:147], 0, v[170:171]
	v_pk_fma_f32 v[32:33], v[62:63], v[32:33], v[78:79]
	v_pk_fma_f32 v[40:41], v[60:61], v[40:41], v[76:77]
	v_cvt_pk_bf16_f32 v40, v40, v41
	v_cvt_pk_bf16_f32 v41, v32, v33
	v_lshl_add_u64 v[32:33], v[148:149], 0, v[182:183]
	flat_store_dwordx2 v[32:33], v[40:41]
.LBB0_1077:
	s_or_b64 exec, exec, s[0:1]
	flat_load_dwordx4 v[72:75], v[98:99]
	flat_load_dwordx4 v[64:67], v[82:83] offset:2048
	flat_load_dwordx4 v[68:71], v[84:85] offset:2048
	flat_load_dwordx4 v[60:63], v[86:87]
	v_pk_mul_f32 v[48:49], v[58:59], v[176:177]
	s_mov_b64 s[0:1], 0xb828800
	v_pk_mul_f32 v[40:41], v[200:201], v[24:25]
	v_add_co_u32_e32 v76, vcc, 0xf828000, v184
	v_lshl_add_u64 v[78:79], v[172:173], 0, s[0:1]
	s_nop 0
	v_addc_co_u32_e32 v77, vcc, 0, v185, vcc
	s_waitcnt vmcnt(0) lgkmcnt(0)
	v_pk_add_f32 v[32:33], v[72:73], 1.0 op_sel_hi:[1,0]
	v_pk_add_f32 v[24:25], v[74:75], 1.0 op_sel_hi:[1,0]
	v_pk_fma_f32 v[56:57], v[48:49], v[64:65], v[68:69]
	v_pk_fma_f32 v[58:59], v[40:41], v[66:67], v[70:71]
	v_pk_fma_f32 v[48:49], v[56:57], v[32:33], v[60:61]
	v_pk_fma_f32 v[40:41], v[58:59], v[24:25], v[62:63]
	v_cvt_pk_bf16_f32 v48, v48, v49
	s_nop 0
	v_cvt_pk_bf16_f32 v49, v40, v41
	flat_store_dwordx2 v[76:77], v[48:49] offset:1024
	s_and_saveexec_b64 s[0:1], s[4:5]
	s_cbranch_execz .LBB0_1079
	v_pk_mul_f32 v[40:41], v[52:53], v[0:1] op_sel_hi:[1,0]
	v_pk_mul_f32 v[48:49], v[54:55], v[0:1] op_sel_hi:[1,0]
	v_pk_fma_f32 v[54:55], v[40:41], v[66:67], v[70:71]
	v_pk_fma_f32 v[52:53], v[48:49], v[64:65], v[68:69]
	v_lshl_add_u64 v[40:41], v[136:137], 0, v[170:171]
	v_pk_fma_f32 v[24:25], v[54:55], v[24:25], v[62:63]
	v_pk_fma_f32 v[32:33], v[52:53], v[32:33], v[60:61]
	v_cvt_pk_bf16_f32 v32, v32, v33
	v_cvt_pk_bf16_f32 v33, v24, v25
	v_lshl_add_u64 v[24:25], v[150:151], 0, v[182:183]
	flat_store_dwordx2 v[24:25], v[32:33]
; __device__ __forceinline__ unsigned cvt_pk_bf16(float lo, float hi) { unsigned r; asm volatile("v_cvt_pk_bf16_f32 %0, %1, %2" : "=v"(r) : "v"(lo), "v"(hi)); return r; }
; __device__ __forceinline__ void phase_ln(const float* z, float* xo, const float* __restrict__ g, const float* __restrict__ b, const float* __restrict__ sc, const float* __restrict__ sh, bf16_t* __restrict__ u) {
;     ...
;         for (int j = 0; j < 8; ++j) { const int col = j * 256 + 4 * lane;
;             const f32x4 gg = *(const f32x4*)(g + col), bb = *(const f32x4*)(b + col);
;             f32x4 s1 = {0.f, 0.f, 0.f, 0.f}, h1 = {0.f, 0.f, 0.f, 0.f};
;             if (u) { s1 = *(const f32x4*)(sc + col) + 1.0f; h1 = *(const f32x4*)(sh + col); }
; #pragma unroll
;             for (int k = 0; k < 2; ++k) { if (k == 1 && !hasB) continue;
;                 const f32x4 o = (v[k][j] - mean[k]) * rstd[k] * gg + bb;
;                 *(f32x4*)(xo + (size_t)rr[k] * DM + col) = o;
;                 if (u) { const f32x4 m = o * s1 + h1; u32x2 w; w.x = cvt_pk_bf16(m[0], m[1]); w.y = cvt_pk_bf16(m[2], m[3]); *(u32x2*)(u + (size_t)rr[k] * DM + col) = w; } } }
.LBB0_1079:
	s_or_b64 exec, exec, s[0:1]
	flat_load_dwordx4 v[52:55], v[82:83] offset:3072
	flat_load_dwordx4 v[56:59], v[84:85] offset:3072
	flat_load_dwordx4 v[60:63], v[100:101]
	v_mov_b32_e32 v24, v176
	v_mov_b32_e32 v25, v176
	s_mov_b64 s[0:1], 0xb828c00
	v_pk_mul_f32 v[48:49], v[196:197], v[24:25]
	v_pk_mul_f32 v[66:67], v[50:51], v[176:177]
	v_lshl_add_u64 v[64:65], v[172:173], 0, s[0:1]
	s_waitcnt vmcnt(0) lgkmcnt(0)
	v_pk_fma_f32 v[50:51], v[48:49], v[54:55], v[58:59]
	v_pk_add_f32 v[32:33], v[62:63], 1.0 op_sel_hi:[1,0]
	v_pk_add_f32 v[40:41], v[60:61], 1.0 op_sel_hi:[1,0]
	flat_load_dwordx4 v[60:63], v[88:89]
	v_pk_fma_f32 v[48:49], v[66:67], v[52:53], v[56:57]
	s_waitcnt vmcnt(0) lgkmcnt(0)
	s_nop 0
	v_pk_fma_f32 v[50:51], v[50:51], v[32:33], v[62:63]
	v_pk_fma_f32 v[48:49], v[48:49], v[40:41], v[60:61]
	s_nop 0
	v_cvt_pk_bf16_f32 v48, v48, v49
	v_cvt_pk_bf16_f32 v49, v50, v51
	v_add_co_u32_e32 v50, vcc, 0xf828000, v184
	s_nop 1
	v_addc_co_u32_e32 v51, vcc, 0, v185, vcc
	flat_store_dwordx2 v[50:51], v[48:49] offset:1536
	s_and_saveexec_b64 s[0:1], s[4:5]
	s_cbranch_execz .LBB0_1081
	v_pk_mul_f32 v[44:45], v[44:45], v[0:1] op_sel_hi:[1,0]
	v_pk_mul_f32 v[48:49], v[46:47], v[0:1] op_sel_hi:[1,0]
	v_pk_fma_f32 v[46:47], v[44:45], v[54:55], v[58:59]
	v_pk_fma_f32 v[44:45], v[48:49], v[52:53], v[56:57]
	v_lshl_add_u64 v[48:49], v[138:139], 0, v[170:171]
	v_pk_fma_f32 v[32:33], v[46:47], v[32:33], v[62:63]
	v_pk_fma_f32 v[40:41], v[44:45], v[40:41], v[60:61]
	v_cvt_pk_bf16_f32 v40, v40, v41
	v_cvt_pk_bf16_f32 v41, v32, v33
	v_lshl_add_u64 v[32:33], v[152:153], 0, v[182:183]
	flat_store_dwordx2 v[32:33], v[40:41]
.LBB0_1081:
	s_or_b64 exec, exec, s[0:1]
	flat_load_dwordx4 v[56:59], v[102:103]
	flat_load_dwordx4 v[48:51], v[118:119]
	flat_load_dwordx4 v[52:55], v[110:111]
	flat_load_dwordx4 v[44:47], v[90:91]
	s_mov_b64 s[0:1], 0xb829000
	v_pk_mul_f32 v[40:41], v[194:195], v[24:25]
	v_pk_mul_f32 v[60:61], v[42:43], v[176:177]
	v_add_co_u32_e32 v62, vcc, 0xf828000, v184
	v_lshl_add_u64 v[64:65], v[172:173], 0, s[0:1]
	s_nop 0
	v_addc_co_u32_e32 v63, vcc, 0, v185, vcc
	s_waitcnt vmcnt(0) lgkmcnt(0)
	v_pk_add_f32 v[32:33], v[56:57], 1.0 op_sel_hi:[1,0]
	v_pk_add_f32 v[24:25], v[58:59], 1.0 op_sel_hi:[1,0]
	v_pk_fma_f32 v[42:43], v[40:41], v[50:51], v[54:55]
	v_pk_fma_f32 v[40:41], v[60:61], v[48:49], v[52:53]
	s_nop 1
	v_pk_fma_f32 v[40:41], v[40:41], v[32:33], v[44:45]
	v_pk_fma_f32 v[42:43], v[42:43], v[24:25], v[46:47]
	v_cvt_pk_bf16_f32 v40, v40, v41
	s_nop 0
	v_cvt_pk_bf16_f32 v41, v42, v43
	flat_store_dwordx2 v[62:63], v[40:41] offset:2048
	s_and_saveexec_b64 s[0:1], s[4:5]
	s_cbranch_execz .LBB0_1083
	v_pk_mul_f32 v[36:37], v[36:37], v[0:1] op_sel_hi:[1,0]
	v_pk_mul_f32 v[40:41], v[38:39], v[0:1] op_sel_hi:[1,0]
	v_pk_fma_f32 v[38:39], v[36:37], v[50:51], v[54:55]
	v_pk_fma_f32 v[36:37], v[40:41], v[48:49], v[52:53]
	v_lshl_add_u64 v[40:41], v[128:129], 0, v[170:171]
	v_pk_fma_f32 v[24:25], v[38:39], v[24:25], v[46:47]
	v_pk_fma_f32 v[32:33], v[36:37], v[32:33], v[44:45]
	v_cvt_pk_bf16_f32 v32, v32, v33
	v_cvt_pk_bf16_f32 v33, v24, v25
	v_lshl_add_u64 v[24:25], v[158:159], 0, v[182:183]
	flat_store_dwordx2 v[24:25], v[32:33]
; __device__ __forceinline__ unsigned cvt_pk_bf16(float lo, float hi) { unsigned r; asm volatile("v_cvt_pk_bf16_f32 %0, %1, %2" : "=v"(r) : "v"(lo), "v"(hi)); return r; }
; __device__ __forceinline__ void phase_ln(const float* z, float* xo, const float* __restrict__ g, const float* __restrict__ b, const float* __restrict__ sc, const float* __restrict__ sh, bf16_t* __restrict__ u) {
;     ...
;         for (int j = 0; j < 8; ++j) { const int col = j * 256 + 4 * lane;
;             const f32x4 gg = *(const f32x4*)(g + col), bb = *(const f32x4*)(b + col);
;             f32x4 s1 = {0.f, 0.f, 0.f, 0.f}, h1 = {0.f, 0.f, 0.f, 0.f};
;             if (u) { s1 = *(const f32x4*)(sc + col) + 1.0f; h1 = *(const f32x4*)(sh + col); }
; #pragma unroll
;             for (int k = 0; k < 2; ++k) { if (k == 1 && !hasB) continue;
;                 const f32x4 o = (v[k][j] - mean[k]) * rstd[k] * gg + bb;
;                 *(f32x4*)(xo + (size_t)rr[k] * DM + col) = o;
;                 if (u) { const f32x4 m = o * s1 + h1; u32x2 w; w.x = cvt_pk_bf16(m[0], m[1]); w.y = cvt_pk_bf16(m[2], m[3]); *(u32x2*)(u + (size_t)rr[k] * DM + col) = w; } } }
.LBB0_1083:
	s_or_b64 exec, exec, s[0:1]
	flat_load_dwordx4 v[36:39], v[120:121]
	flat_load_dwordx4 v[40:43], v[112:113]
	flat_load_dwordx4 v[44:47], v[104:105]
	v_mov_b32_e32 v24, v176
	v_mov_b32_e32 v25, v176
	s_mov_b64 s[0:1], 0xb829400
	v_pk_mul_f32 v[50:51], v[180:181], v[24:25]
	v_pk_mul_f32 v[34:35], v[34:35], v[176:177]
	v_lshl_add_u64 v[54:55], v[172:173], 0, s[0:1]
	s_waitcnt vmcnt(0) lgkmcnt(0)
	v_pk_fma_f32 v[52:53], v[50:51], v[38:39], v[42:43]
	v_pk_add_f32 v[32:33], v[46:47], 1.0 op_sel_hi:[1,0]
	v_pk_add_f32 v[48:49], v[44:45], 1.0 op_sel_hi:[1,0]
	flat_load_dwordx4 v[44:47], v[92:93]
	v_pk_fma_f32 v[50:51], v[34:35], v[36:37], v[40:41]
	s_waitcnt vmcnt(0) lgkmcnt(0)
	v_pk_fma_f32 v[34:35], v[52:53], v[32:33], v[46:47]
	v_pk_fma_f32 v[50:51], v[50:51], v[48:49], v[44:45]
	s_nop 0
	v_cvt_pk_bf16_f32 v50, v50, v51
	v_cvt_pk_bf16_f32 v51, v34, v35
	v_add_co_u32_e32 v34, vcc, 0xf828000, v184
	s_nop 1
	v_addc_co_u32_e32 v35, vcc, 0, v185, vcc
	flat_store_dwordx2 v[34:35], v[50:51] offset:2560
	s_and_saveexec_b64 s[0:1], s[4:5]
	s_cbranch_execz .LBB0_1085
	v_pk_mul_f32 v[28:29], v[28:29], v[0:1] op_sel_hi:[1,0]
	v_pk_mul_f32 v[34:35], v[30:31], v[0:1] op_sel_hi:[1,0]
	v_pk_fma_f32 v[30:31], v[28:29], v[38:39], v[42:43]
	v_pk_fma_f32 v[28:29], v[34:35], v[36:37], v[40:41]
	v_lshl_add_u64 v[34:35], v[130:131], 0, v[170:171]
	s_nop 1
	v_pk_fma_f32 v[30:31], v[30:31], v[32:33], v[46:47]
	v_pk_fma_f32 v[28:29], v[28:29], v[48:49], v[44:45]
	s_nop 0
	v_cvt_pk_bf16_f32 v28, v28, v29
	v_cvt_pk_bf16_f32 v29, v30, v31
	v_lshl_add_u64 v[30:31], v[160:161], 0, v[182:183]
	flat_store_dwordx2 v[30:31], v[28:29]
.LBB0_1085:
	s_or_b64 exec, exec, s[0:1]
	flat_load_dwordx4 v[40:43], v[106:107]
	flat_load_dwordx4 v[32:35], v[122:123]
	flat_load_dwordx4 v[36:39], v[114:115]
	flat_load_dwordx4 v[28:31], v[94:95]
	s_mov_b64 s[0:1], 0xb829800
	v_pk_mul_f32 v[44:45], v[178:179], v[24:25]
	v_pk_mul_f32 v[46:47], v[26:27], v[176:177]
	v_add_co_u32_e32 v48, vcc, 0xf828000, v184
	v_lshl_add_u64 v[50:51], v[172:173], 0, s[0:1]
	s_nop 0
	v_addc_co_u32_e32 v49, vcc, 0, v185, vcc
	s_waitcnt vmcnt(0) lgkmcnt(0)
	v_pk_add_f32 v[24:25], v[42:43], 1.0 op_sel_hi:[1,0]
	v_pk_add_f32 v[26:27], v[40:41], 1.0 op_sel_hi:[1,0]
	v_pk_fma_f32 v[42:43], v[44:45], v[34:35], v[38:39]
	v_pk_fma_f32 v[40:41], v[46:47], v[32:33], v[36:37]
	s_nop 1
	v_pk_fma_f32 v[40:41], v[40:41], v[26:27], v[28:29]
	v_pk_fma_f32 v[42:43], v[42:43], v[24:25], v[30:31]
	v_cvt_pk_bf16_f32 v40, v40, v41
	s_nop 0
	v_cvt_pk_bf16_f32 v41, v42, v43
	flat_store_dwordx2 v[48:49], v[40:41] offset:3072
	s_and_saveexec_b64 s[0:1], s[4:5]
	s_cbranch_execz .LBB0_1087
	v_pk_mul_f32 v[20:21], v[20:21], v[0:1] op_sel_hi:[1,0]
	v_pk_mul_f32 v[40:41], v[22:23], v[0:1] op_sel_hi:[1,0]
	v_pk_fma_f32 v[22:23], v[20:21], v[34:35], v[38:39]
	v_pk_fma_f32 v[20:21], v[40:41], v[32:33], v[36:37]
	v_lshl_add_u64 v[32:33], v[132:133], 0, v[170:171]
	s_nop 1
	v_pk_fma_f32 v[22:23], v[22:23], v[24:25], v[30:31]
	v_pk_fma_f32 v[20:21], v[20:21], v[26:27], v[28:29]
	s_nop 0
	v_cvt_pk_bf16_f32 v20, v20, v21
	v_cvt_pk_bf16_f32 v21, v22, v23
	v_lshl_add_u64 v[22:23], v[162:163], 0, v[182:183]
	flat_store_dwordx2 v[22:23], v[20:21]
.LBB0_1087:
	s_or_b64 exec, exec, s[0:1]
	flat_load_dwordx4 v[32:35], v[108:109]
	flat_load_dwordx4 v[24:27], v[124:125]
	flat_load_dwordx4 v[28:31], v[116:117]
	flat_load_dwordx4 v[20:23], v[96:97]
	v_mov_b32_e32 v36, v176
	v_mov_b32_e32 v37, v176
	s_mov_b64 s[0:1], 0xb829c00
	v_pk_mul_f32 v[40:41], v[18:19], v[176:177]
	v_pk_mul_f32 v[36:37], v[174:175], v[36:37]
	v_lshl_add_u64 v[38:39], v[172:173], 0, s[0:1]
	v_add_co_u32_e32 v42, vcc, 0xf828000, v184
	s_waitcnt vmcnt(0) lgkmcnt(0)
	v_pk_add_f32 v[18:19], v[34:35], 1.0 op_sel_hi:[1,0]
	v_pk_add_f32 v[32:33], v[32:33], 1.0 op_sel_hi:[1,0]
	v_pk_fma_f32 v[36:37], v[36:37], v[26:27], v[30:31]
	v_pk_fma_f32 v[34:35], v[40:41], v[24:25], v[28:29]
	v_addc_co_u32_e32 v43, vcc, 0, v185, vcc
	s_nop 0
	v_pk_fma_f32 v[34:35], v[34:35], v[32:33], v[20:21]
	v_pk_fma_f32 v[36:37], v[36:37], v[18:19], v[22:23]
	v_cvt_pk_bf16_f32 v34, v34, v35
	s_nop 0
	v_cvt_pk_bf16_f32 v35, v36, v37
	flat_store_dwordx2 v[42:43], v[34:35] offset:3584
	s_and_saveexec_b64 s[0:1], s[4:5]
	s_cbranch_execz .LBB0_1072
	v_pk_mul_f32 v[16:17], v[16:17], v[0:1] op_sel_hi:[1,0]
	v_pk_mul_f32 v[14:15], v[14:15], v[0:1] op_sel_hi:[1,0]
	v_pk_fma_f32 v[16:17], v[16:17], v[26:27], v[30:31]
	v_pk_fma_f32 v[14:15], v[14:15], v[24:25], v[28:29]
	v_lshl_add_u64 v[24:25], v[134:135], 0, v[170:171]
	s_nop 1
	v_pk_fma_f32 v[16:17], v[16:17], v[18:19], v[22:23]
	v_pk_fma_f32 v[14:15], v[14:15], v[32:33], v[20:21]
	s_nop 0
	v_cvt_pk_bf16_f32 v14, v14, v15
	v_cvt_pk_bf16_f32 v15, v16, v17
	v_lshl_add_u64 v[16:17], v[164:165], 0, v[182:183]
	flat_store_dwordx2 v[16:17], v[14:15]
	s_branch .LBB0_1072

;     __device__ __forceinline__ void operator()(const f32x4 (&acc)[2][2][4][2], const Unit& u, int wr, int wc, int fr, int fq) const {
;         const int row0 = u.pm * BM + wr * 64 + fr, col0 = u.pn * BM + wc * 32 + 4 * fq;
;         f32x4 gv[2][2];
; #pragma unroll
;         for (int bj = 0; bj < 2; ++bj)
; #pragma unroll
;             for (int n = 0; n < 2; ++n) gv[bj][n] = *(const f32x4*)(gate + col0 + bj * HALF + n * 16) + 1.0f;
; #pragma unroll
;         for (int ai = 0; ai < 2; ++ai)
; #pragma unroll
;             for (int m = 0; m < 4; ++m) { const size_t off = (size_t)(row0 + ai * HALF + m * 16) * ldc + col0;
; #pragma unroll
;                 for (int bj = 0; bj < 2; ++bj)
; #pragma unroll
;                     for (int n = 0; n < 2; ++n) { const f32x4 xr = *(const f32x4*)(xres + off + bj * HALF + n * 16);
;                         *(f32x4*)(z + off + bj * HALF + n * 16) = xr * alpha + gv[bj][n] * acc[ai][bj][m][n]; }
;                 if (m == 3) asm volatile("" ::: "memory"); }
; __device__ __forceinline__ void phase_ln(const float* z, float* xo, const float* __restrict__ g, const float* __restrict__ b, const float* __restrict__ sc, const float* __restrict__ sh, bf16_t* __restrict__ u) {
;     ...
;                 const f32x4 o = (v[k][j] - mean[k]) * rstd[k] * gg + bb;
.LBB0_1271:
	v_lshl_or_b32 v158, s58, 8, v164
	v_ashrrev_i32_e32 v159, 31, v158
	v_mov_b32_e32 v212, 0x20068
	ds_read2_b64 v[236:239], v212 offset1:1
	v_readlane_b32 s24, v254, 46
	v_lshl_add_u64 v[178:179], v[158:159], 2, s[16:17]
	v_lshl_add_u32 v160, s57, 8, v162
	v_ashrrev_i32_e32 v161, 31, v160
	s_lshl_b32 s24, s24, 11
	s_nop 1
	v_add_u32_e32 v212, s24, v158
	v_mov_b32_e32 v213, 0
	s_sub_u32 s24, s14, 0x10000
	s_subb_u32 s25, s15, 0
	v_lshlrev_b32_e32 v184, 3, v160
	global_load_dwordx2 v[140:141], v184, s[24:25]
	global_load_dwordx2 v[142:143], v184, s[24:25] offset:128
	global_load_dwordx2 v[144:145], v184, s[24:25] offset:256
	global_load_dwordx2 v[146:147], v184, s[24:25] offset:384
	global_load_dwordx2 v[148:149], v184, s[24:25] offset:1024
	global_load_dwordx2 v[150:151], v184, s[24:25] offset:1152
	global_load_dwordx2 v[152:153], v184, s[24:25] offset:1280
	global_load_dwordx2 v[154:155], v184, s[24:25] offset:1408
	v_lshlrev_b64 v[156:157], 11, v[160:161]
	v_lshl_add_u64 v[156:157], v[156:157], 0, v[158:159]
	v_lshlrev_b64 v[156:157], 2, v[156:157]
	v_lshl_add_u64 v[156:157], s[14:15], 0, v[156:157]
	s_mov_b32 s26, 0x3fb504f3
	s_mov_b32 s27, 0xba000000
	s_waitcnt lgkmcnt(0)
	v_lshl_add_u64 v[180:181], v[212:213], 2, v[236:237]
	v_lshl_add_u64 v[210:211], v[212:213], 2, v[238:239]
	global_load_dwordx4 v[166:169], v[178:179], off
	global_load_dwordx4 v[170:173], v[180:181], off
	global_load_dwordx4 v[174:177], v[210:211], off
	v_mov_b64_e32 v[182:183], v[156:157]
	s_mov_b64 s[24:25], 0x20000
	v_mov_b64_e32 v[184:185], v[182:183]
	global_load_dwordx4 v[194:197], v[182:183], off
	v_lshl_add_u64 v[182:183], v[182:183], 0, s[24:25]
	global_load_dwordx4 v[198:201], v[182:183], off
	v_lshl_add_u64 v[182:183], v[182:183], 0, s[24:25]
	global_load_dwordx4 v[202:205], v[182:183], off
	v_lshl_add_u64 v[182:183], v[182:183], 0, s[24:25]
	global_load_dwordx4 v[206:209], v[182:183], off
	s_waitcnt vmcnt(0)
	v_pk_add_f32 v[166:167], v[166:167], 1.0 op_sel_hi:[1,0]
	v_pk_add_f32 v[168:169], v[168:169], 1.0 op_sel_hi:[1,0]
	v_pk_fma_f32 v[194:195], v[140:141], s[26:27], v[194:195] op_sel:[0,1,0] op_sel_hi:[0,1,1]
	v_pk_mul_f32 v[194:195], v[194:195], v[140:141] op_sel:[0,1] op_sel_hi:[1,1]
	v_pk_fma_f32 v[194:195], v[170:171], v[194:195], v[174:175]
	v_pk_mul_f32 v[194:195], v[194:195], s[26:27] op_sel_hi:[1,0]
	v_pk_fma_f32 v[126:127], v[126:127], v[166:167], v[194:195]
	v_pk_fma_f32 v[196:197], v[140:141], s[26:27], v[196:197] op_sel:[0,1,0] op_sel_hi:[0,1,1]
	v_pk_mul_f32 v[196:197], v[196:197], v[140:141] op_sel:[0,1] op_sel_hi:[1,1]
	v_pk_fma_f32 v[196:197], v[172:173], v[196:197], v[176:177]
	v_pk_mul_f32 v[196:197], v[196:197], s[26:27] op_sel_hi:[1,0]
	v_pk_fma_f32 v[128:129], v[128:129], v[168:169], v[196:197]
	global_store_dwordx4 v[184:185], v[126:129], off
	v_lshl_add_u64 v[184:185], v[184:185], 0, s[24:25]
	v_pk_fma_f32 v[198:199], v[142:143], s[26:27], v[198:199] op_sel:[0,1,0] op_sel_hi:[0,1,1]
	v_pk_mul_f32 v[198:199], v[198:199], v[142:143] op_sel:[0,1] op_sel_hi:[1,1]
	v_pk_fma_f32 v[198:199], v[170:171], v[198:199], v[174:175]
	v_pk_mul_f32 v[198:199], v[198:199], s[26:27] op_sel_hi:[1,0]
	v_pk_fma_f32 v[110:111], v[110:111], v[166:167], v[198:199]
	v_pk_fma_f32 v[200:201], v[142:143], s[26:27], v[200:201] op_sel:[0,1,0] op_sel_hi:[0,1,1]
	v_pk_mul_f32 v[200:201], v[200:201], v[142:143] op_sel:[0,1] op_sel_hi:[1,1]
	v_pk_fma_f32 v[200:201], v[172:173], v[200:201], v[176:177]
	v_pk_mul_f32 v[200:201], v[200:201], s[26:27] op_sel_hi:[1,0]
	v_pk_fma_f32 v[112:113], v[112:113], v[168:169], v[200:201]
	global_store_dwordx4 v[184:185], v[110:113], off
	v_lshl_add_u64 v[184:185], v[184:185], 0, s[24:25]
	v_pk_fma_f32 v[202:203], v[144:145], s[26:27], v[202:203] op_sel:[0,1,0] op_sel_hi:[0,1,1]
	v_pk_mul_f32 v[202:203], v[202:203], v[144:145] op_sel:[0,1] op_sel_hi:[1,1]
	v_pk_fma_f32 v[202:203], v[170:171], v[202:203], v[174:175]
	v_pk_mul_f32 v[202:203], v[202:203], s[26:27] op_sel_hi:[1,0]
	v_pk_fma_f32 v[94:95], v[94:95], v[166:167], v[202:203]
	v_pk_fma_f32 v[204:205], v[144:145], s[26:27], v[204:205] op_sel:[0,1,0] op_sel_hi:[0,1,1]
	v_pk_mul_f32 v[204:205], v[204:205], v[144:145] op_sel:[0,1] op_sel_hi:[1,1]
	v_pk_fma_f32 v[204:205], v[172:173], v[204:205], v[176:177]
	v_pk_mul_f32 v[204:205], v[204:205], s[26:27] op_sel_hi:[1,0]
	v_pk_fma_f32 v[96:97], v[96:97], v[168:169], v[204:205]
	global_store_dwordx4 v[184:185], v[94:97], off
	v_lshl_add_u64 v[184:185], v[184:185], 0, s[24:25]
	v_pk_fma_f32 v[206:207], v[146:147], s[26:27], v[206:207] op_sel:[0,1,0] op_sel_hi:[0,1,1]
	v_pk_mul_f32 v[206:207], v[206:207], v[146:147] op_sel:[0,1] op_sel_hi:[1,1]
	v_pk_fma_f32 v[206:207], v[170:171], v[206:207], v[174:175]
	v_pk_mul_f32 v[206:207], v[206:207], s[26:27] op_sel_hi:[1,0]
	v_pk_fma_f32 v[78:79], v[78:79], v[166:167], v[206:207]
	v_pk_fma_f32 v[208:209], v[146:147], s[26:27], v[208:209] op_sel:[0,1,0] op_sel_hi:[0,1,1]
	v_pk_mul_f32 v[208:209], v[208:209], v[146:147] op_sel:[0,1] op_sel_hi:[1,1]
	v_pk_fma_f32 v[208:209], v[172:173], v[208:209], v[176:177]
	v_pk_mul_f32 v[208:209], v[208:209], s[26:27] op_sel_hi:[1,0]
	v_pk_fma_f32 v[80:81], v[80:81], v[168:169], v[208:209]
	global_store_dwordx4 v[184:185], v[78:81], off
	s_mov_b64 s[24:25], 0x100000
	v_lshl_add_u64 v[182:183], v[156:157], 0, s[24:25]
	s_mov_b64 s[24:25], 0x20000
	v_mov_b64_e32 v[184:185], v[182:183]
	global_load_dwordx4 v[194:197], v[182:183], off
	v_lshl_add_u64 v[182:183], v[182:183], 0, s[24:25]
	global_load_dwordx4 v[198:201], v[182:183], off
	v_lshl_add_u64 v[182:183], v[182:183], 0, s[24:25]
	global_load_dwordx4 v[202:205], v[182:183], off
	v_lshl_add_u64 v[182:183], v[182:183], 0, s[24:25]
	global_load_dwordx4 v[206:209], v[182:183], off
	s_waitcnt vmcnt(0)
;     __device__ __forceinline__ void operator()(const f32x4 (&acc)[2][2][4][2], const Unit& u, int wr, int wc, int fr, int fq) const {
;     ...
;             for (int m = 0; m < 4; ++m) { const size_t off = (size_t)(row0 + ai * HALF + m * 16) * ldc + col0;
; #pragma unroll
;                 for (int bj = 0; bj < 2; ++bj)
; #pragma unroll
;                     for (int n = 0; n < 2; ++n) { const f32x4 xr = *(const f32x4*)(xres + off + bj * HALF + n * 16);
;                         *(f32x4*)(z + off + bj * HALF + n * 16) = xr * alpha + gv[bj][n] * acc[ai][bj][m][n]; }
;                 if (m == 3) asm volatile("" ::: "memory"); }
; __device__ __forceinline__ void phase_ln(const float* z, float* xo, const float* __restrict__ g, const float* __restrict__ b, const float* __restrict__ sc, const float* __restrict__ sh, bf16_t* __restrict__ u) {
;     ...
;                 const f32x4 o = (v[k][j] - mean[k]) * rstd[k] * gg + bb;
	v_pk_fma_f32 v[194:195], v[148:149], s[26:27], v[194:195] op_sel:[0,1,0] op_sel_hi:[0,1,1]
	v_pk_mul_f32 v[194:195], v[194:195], v[148:149] op_sel:[0,1] op_sel_hi:[1,1]
	v_pk_fma_f32 v[194:195], v[170:171], v[194:195], v[174:175]
	v_pk_mul_f32 v[194:195], v[194:195], s[26:27] op_sel_hi:[1,0]
	v_pk_fma_f32 v[62:63], v[62:63], v[166:167], v[194:195]
	v_pk_fma_f32 v[196:197], v[148:149], s[26:27], v[196:197] op_sel:[0,1,0] op_sel_hi:[0,1,1]
	v_pk_mul_f32 v[196:197], v[196:197], v[148:149] op_sel:[0,1] op_sel_hi:[1,1]
	v_pk_fma_f32 v[196:197], v[172:173], v[196:197], v[176:177]
	v_pk_mul_f32 v[196:197], v[196:197], s[26:27] op_sel_hi:[1,0]
	v_pk_fma_f32 v[64:65], v[64:65], v[168:169], v[196:197]
	global_store_dwordx4 v[184:185], v[62:65], off
	v_lshl_add_u64 v[184:185], v[184:185], 0, s[24:25]
	v_pk_fma_f32 v[198:199], v[150:151], s[26:27], v[198:199] op_sel:[0,1,0] op_sel_hi:[0,1,1]
	v_pk_mul_f32 v[198:199], v[198:199], v[150:151] op_sel:[0,1] op_sel_hi:[1,1]
	v_pk_fma_f32 v[198:199], v[170:171], v[198:199], v[174:175]
	v_pk_mul_f32 v[198:199], v[198:199], s[26:27] op_sel_hi:[1,0]
	v_pk_fma_f32 v[46:47], v[46:47], v[166:167], v[198:199]
	v_pk_fma_f32 v[200:201], v[150:151], s[26:27], v[200:201] op_sel:[0,1,0] op_sel_hi:[0,1,1]
	v_pk_mul_f32 v[200:201], v[200:201], v[150:151] op_sel:[0,1] op_sel_hi:[1,1]
	v_pk_fma_f32 v[200:201], v[172:173], v[200:201], v[176:177]
	v_pk_mul_f32 v[200:201], v[200:201], s[26:27] op_sel_hi:[1,0]
	v_pk_fma_f32 v[48:49], v[48:49], v[168:169], v[200:201]
	global_store_dwordx4 v[184:185], v[46:49], off
	v_lshl_add_u64 v[184:185], v[184:185], 0, s[24:25]
	v_pk_fma_f32 v[202:203], v[152:153], s[26:27], v[202:203] op_sel:[0,1,0] op_sel_hi:[0,1,1]
	v_pk_mul_f32 v[202:203], v[202:203], v[152:153] op_sel:[0,1] op_sel_hi:[1,1]
	v_pk_fma_f32 v[202:203], v[170:171], v[202:203], v[174:175]
	v_pk_mul_f32 v[202:203], v[202:203], s[26:27] op_sel_hi:[1,0]
	v_pk_fma_f32 v[30:31], v[30:31], v[166:167], v[202:203]
	v_pk_fma_f32 v[204:205], v[152:153], s[26:27], v[204:205] op_sel:[0,1,0] op_sel_hi:[0,1,1]
	v_pk_mul_f32 v[204:205], v[204:205], v[152:153] op_sel:[0,1] op_sel_hi:[1,1]
	v_pk_fma_f32 v[204:205], v[172:173], v[204:205], v[176:177]
	v_pk_mul_f32 v[204:205], v[204:205], s[26:27] op_sel_hi:[1,0]
	v_pk_fma_f32 v[32:33], v[32:33], v[168:169], v[204:205]
	global_store_dwordx4 v[184:185], v[30:33], off
	v_lshl_add_u64 v[184:185], v[184:185], 0, s[24:25]
	v_pk_fma_f32 v[206:207], v[154:155], s[26:27], v[206:207] op_sel:[0,1,0] op_sel_hi:[0,1,1]
	v_pk_mul_f32 v[206:207], v[206:207], v[154:155] op_sel:[0,1] op_sel_hi:[1,1]
	v_pk_fma_f32 v[206:207], v[170:171], v[206:207], v[174:175]
	v_pk_mul_f32 v[206:207], v[206:207], s[26:27] op_sel_hi:[1,0]
	v_pk_fma_f32 v[14:15], v[14:15], v[166:167], v[206:207]
	v_pk_fma_f32 v[208:209], v[154:155], s[26:27], v[208:209] op_sel:[0,1,0] op_sel_hi:[0,1,1]
	v_pk_mul_f32 v[208:209], v[208:209], v[154:155] op_sel:[0,1] op_sel_hi:[1,1]
	v_pk_fma_f32 v[208:209], v[172:173], v[208:209], v[176:177]
	v_pk_mul_f32 v[208:209], v[208:209], s[26:27] op_sel_hi:[1,0]
	v_pk_fma_f32 v[16:17], v[16:17], v[168:169], v[208:209]
	global_store_dwordx4 v[184:185], v[14:17], off
	global_load_dwordx4 v[166:169], v[178:179], off offset:64
	global_load_dwordx4 v[170:173], v[180:181], off offset:64
	global_load_dwordx4 v[174:177], v[210:211], off offset:64
	v_mov_b64_e32 v[182:183], v[156:157]
	s_mov_b64 s[24:25], 0x20000
	v_mov_b64_e32 v[184:185], v[182:183]
	global_load_dwordx4 v[194:197], v[182:183], off offset:64
	v_lshl_add_u64 v[182:183], v[182:183], 0, s[24:25]
	global_load_dwordx4 v[198:201], v[182:183], off offset:64
	v_lshl_add_u64 v[182:183], v[182:183], 0, s[24:25]
	global_load_dwordx4 v[202:205], v[182:183], off offset:64
	v_lshl_add_u64 v[182:183], v[182:183], 0, s[24:25]
	global_load_dwordx4 v[206:209], v[182:183], off offset:64
	s_waitcnt vmcnt(0)
	v_pk_add_f32 v[166:167], v[166:167], 1.0 op_sel_hi:[1,0]
	v_pk_add_f32 v[168:169], v[168:169], 1.0 op_sel_hi:[1,0]
	v_pk_fma_f32 v[194:195], v[140:141], s[26:27], v[194:195] op_sel:[0,1,0] op_sel_hi:[0,1,1]
	v_pk_mul_f32 v[194:195], v[194:195], v[140:141] op_sel:[0,1] op_sel_hi:[1,1]
	v_pk_fma_f32 v[194:195], v[170:171], v[194:195], v[174:175]
	v_pk_mul_f32 v[194:195], v[194:195], s[26:27] op_sel_hi:[1,0]
	v_pk_fma_f32 v[122:123], v[122:123], v[166:167], v[194:195]
	v_pk_fma_f32 v[196:197], v[140:141], s[26:27], v[196:197] op_sel:[0,1,0] op_sel_hi:[0,1,1]
	v_pk_mul_f32 v[196:197], v[196:197], v[140:141] op_sel:[0,1] op_sel_hi:[1,1]
	v_pk_fma_f32 v[196:197], v[172:173], v[196:197], v[176:177]
	v_pk_mul_f32 v[196:197], v[196:197], s[26:27] op_sel_hi:[1,0]
	v_pk_fma_f32 v[124:125], v[124:125], v[168:169], v[196:197]
	global_store_dwordx4 v[184:185], v[122:125], off offset:64
	v_lshl_add_u64 v[184:185], v[184:185], 0, s[24:25]
	v_pk_fma_f32 v[198:199], v[142:143], s[26:27], v[198:199] op_sel:[0,1,0] op_sel_hi:[0,1,1]
	v_pk_mul_f32 v[198:199], v[198:199], v[142:143] op_sel:[0,1] op_sel_hi:[1,1]
	v_pk_fma_f32 v[198:199], v[170:171], v[198:199], v[174:175]
	v_pk_mul_f32 v[198:199], v[198:199], s[26:27] op_sel_hi:[1,0]
	v_pk_fma_f32 v[106:107], v[106:107], v[166:167], v[198:199]
	v_pk_fma_f32 v[200:201], v[142:143], s[26:27], v[200:201] op_sel:[0,1,0] op_sel_hi:[0,1,1]
	v_pk_mul_f32 v[200:201], v[200:201], v[142:143] op_sel:[0,1] op_sel_hi:[1,1]
	v_pk_fma_f32 v[200:201], v[172:173], v[200:201], v[176:177]
	v_pk_mul_f32 v[200:201], v[200:201], s[26:27] op_sel_hi:[1,0]
	v_pk_fma_f32 v[108:109], v[108:109], v[168:169], v[200:201]
	global_store_dwordx4 v[184:185], v[106:109], off offset:64
	v_lshl_add_u64 v[184:185], v[184:185], 0, s[24:25]
;     __device__ __forceinline__ void operator()(const f32x4 (&acc)[2][2][4][2], const Unit& u, int wr, int wc, int fr, int fq) const {
;     ...
;             for (int m = 0; m < 4; ++m) { const size_t off = (size_t)(row0 + ai * HALF + m * 16) * ldc + col0;
; #pragma unroll
;                 for (int bj = 0; bj < 2; ++bj)
; #pragma unroll
;                     for (int n = 0; n < 2; ++n) { const f32x4 xr = *(const f32x4*)(xres + off + bj * HALF + n * 16);
;                         *(f32x4*)(z + off + bj * HALF + n * 16) = xr * alpha + gv[bj][n] * acc[ai][bj][m][n]; }
;                 if (m == 3) asm volatile("" ::: "memory"); }
; __device__ __forceinline__ void phase_ln(const float* z, float* xo, const float* __restrict__ g, const float* __restrict__ b, const float* __restrict__ sc, const float* __restrict__ sh, bf16_t* __restrict__ u) {
;     ...
;                 const f32x4 o = (v[k][j] - mean[k]) * rstd[k] * gg + bb;
	v_pk_fma_f32 v[202:203], v[144:145], s[26:27], v[202:203] op_sel:[0,1,0] op_sel_hi:[0,1,1]
	v_pk_mul_f32 v[202:203], v[202:203], v[144:145] op_sel:[0,1] op_sel_hi:[1,1]
	v_pk_fma_f32 v[202:203], v[170:171], v[202:203], v[174:175]
	v_pk_mul_f32 v[202:203], v[202:203], s[26:27] op_sel_hi:[1,0]
	v_pk_fma_f32 v[90:91], v[90:91], v[166:167], v[202:203]
	v_pk_fma_f32 v[204:205], v[144:145], s[26:27], v[204:205] op_sel:[0,1,0] op_sel_hi:[0,1,1]
	v_pk_mul_f32 v[204:205], v[204:205], v[144:145] op_sel:[0,1] op_sel_hi:[1,1]
	v_pk_fma_f32 v[204:205], v[172:173], v[204:205], v[176:177]
	v_pk_mul_f32 v[204:205], v[204:205], s[26:27] op_sel_hi:[1,0]
	v_pk_fma_f32 v[92:93], v[92:93], v[168:169], v[204:205]
	global_store_dwordx4 v[184:185], v[90:93], off offset:64
	v_lshl_add_u64 v[184:185], v[184:185], 0, s[24:25]
	v_pk_fma_f32 v[206:207], v[146:147], s[26:27], v[206:207] op_sel:[0,1,0] op_sel_hi:[0,1,1]
	v_pk_mul_f32 v[206:207], v[206:207], v[146:147] op_sel:[0,1] op_sel_hi:[1,1]
	v_pk_fma_f32 v[206:207], v[170:171], v[206:207], v[174:175]
	v_pk_mul_f32 v[206:207], v[206:207], s[26:27] op_sel_hi:[1,0]
	v_pk_fma_f32 v[74:75], v[74:75], v[166:167], v[206:207]
	v_pk_fma_f32 v[208:209], v[146:147], s[26:27], v[208:209] op_sel:[0,1,0] op_sel_hi:[0,1,1]
	v_pk_mul_f32 v[208:209], v[208:209], v[146:147] op_sel:[0,1] op_sel_hi:[1,1]
	v_pk_fma_f32 v[208:209], v[172:173], v[208:209], v[176:177]
	v_pk_mul_f32 v[208:209], v[208:209], s[26:27] op_sel_hi:[1,0]
	v_pk_fma_f32 v[76:77], v[76:77], v[168:169], v[208:209]
	global_store_dwordx4 v[184:185], v[74:77], off offset:64
	s_mov_b64 s[24:25], 0x100000
	v_lshl_add_u64 v[182:183], v[156:157], 0, s[24:25]
	s_mov_b64 s[24:25], 0x20000
	v_mov_b64_e32 v[184:185], v[182:183]
	global_load_dwordx4 v[194:197], v[182:183], off offset:64
	v_lshl_add_u64 v[182:183], v[182:183], 0, s[24:25]
	global_load_dwordx4 v[198:201], v[182:183], off offset:64
	v_lshl_add_u64 v[182:183], v[182:183], 0, s[24:25]
	global_load_dwordx4 v[202:205], v[182:183], off offset:64
	v_lshl_add_u64 v[182:183], v[182:183], 0, s[24:25]
	global_load_dwordx4 v[206:209], v[182:183], off offset:64
	s_waitcnt vmcnt(0)
	v_pk_fma_f32 v[194:195], v[148:149], s[26:27], v[194:195] op_sel:[0,1,0] op_sel_hi:[0,1,1]
	v_pk_mul_f32 v[194:195], v[194:195], v[148:149] op_sel:[0,1] op_sel_hi:[1,1]
	v_pk_fma_f32 v[194:195], v[170:171], v[194:195], v[174:175]
	v_pk_mul_f32 v[194:195], v[194:195], s[26:27] op_sel_hi:[1,0]
	v_pk_fma_f32 v[58:59], v[58:59], v[166:167], v[194:195]
	v_pk_fma_f32 v[196:197], v[148:149], s[26:27], v[196:197] op_sel:[0,1,0] op_sel_hi:[0,1,1]
	v_pk_mul_f32 v[196:197], v[196:197], v[148:149] op_sel:[0,1] op_sel_hi:[1,1]
	v_pk_fma_f32 v[196:197], v[172:173], v[196:197], v[176:177]
	v_pk_mul_f32 v[196:197], v[196:197], s[26:27] op_sel_hi:[1,0]
	v_pk_fma_f32 v[60:61], v[60:61], v[168:169], v[196:197]
	global_store_dwordx4 v[184:185], v[58:61], off offset:64
	v_lshl_add_u64 v[184:185], v[184:185], 0, s[24:25]
	v_pk_fma_f32 v[198:199], v[150:151], s[26:27], v[198:199] op_sel:[0,1,0] op_sel_hi:[0,1,1]
	v_pk_mul_f32 v[198:199], v[198:199], v[150:151] op_sel:[0,1] op_sel_hi:[1,1]
	v_pk_fma_f32 v[198:199], v[170:171], v[198:199], v[174:175]
	v_pk_mul_f32 v[198:199], v[198:199], s[26:27] op_sel_hi:[1,0]
	v_pk_fma_f32 v[42:43], v[42:43], v[166:167], v[198:199]
	v_pk_fma_f32 v[200:201], v[150:151], s[26:27], v[200:201] op_sel:[0,1,0] op_sel_hi:[0,1,1]
	v_pk_mul_f32 v[200:201], v[200:201], v[150:151] op_sel:[0,1] op_sel_hi:[1,1]
	v_pk_fma_f32 v[200:201], v[172:173], v[200:201], v[176:177]
	v_pk_mul_f32 v[200:201], v[200:201], s[26:27] op_sel_hi:[1,0]
	v_pk_fma_f32 v[44:45], v[44:45], v[168:169], v[200:201]
	global_store_dwordx4 v[184:185], v[42:45], off offset:64
	v_lshl_add_u64 v[184:185], v[184:185], 0, s[24:25]
	v_pk_fma_f32 v[202:203], v[152:153], s[26:27], v[202:203] op_sel:[0,1,0] op_sel_hi:[0,1,1]
	v_pk_mul_f32 v[202:203], v[202:203], v[152:153] op_sel:[0,1] op_sel_hi:[1,1]
	v_pk_fma_f32 v[202:203], v[170:171], v[202:203], v[174:175]
	v_pk_mul_f32 v[202:203], v[202:203], s[26:27] op_sel_hi:[1,0]
	v_pk_fma_f32 v[26:27], v[26:27], v[166:167], v[202:203]
	v_pk_fma_f32 v[204:205], v[152:153], s[26:27], v[204:205] op_sel:[0,1,0] op_sel_hi:[0,1,1]
	v_pk_mul_f32 v[204:205], v[204:205], v[152:153] op_sel:[0,1] op_sel_hi:[1,1]
	v_pk_fma_f32 v[204:205], v[172:173], v[204:205], v[176:177]
	v_pk_mul_f32 v[204:205], v[204:205], s[26:27] op_sel_hi:[1,0]
	v_pk_fma_f32 v[28:29], v[28:29], v[168:169], v[204:205]
	global_store_dwordx4 v[184:185], v[26:29], off offset:64
	v_lshl_add_u64 v[184:185], v[184:185], 0, s[24:25]
	v_pk_fma_f32 v[206:207], v[154:155], s[26:27], v[206:207] op_sel:[0,1,0] op_sel_hi:[0,1,1]
	v_pk_mul_f32 v[206:207], v[206:207], v[154:155] op_sel:[0,1] op_sel_hi:[1,1]
	v_pk_fma_f32 v[206:207], v[170:171], v[206:207], v[174:175]
	v_pk_mul_f32 v[206:207], v[206:207], s[26:27] op_sel_hi:[1,0]
	v_pk_fma_f32 v[10:11], v[10:11], v[166:167], v[206:207]
	v_pk_fma_f32 v[208:209], v[154:155], s[26:27], v[208:209] op_sel:[0,1,0] op_sel_hi:[0,1,1]
	v_pk_mul_f32 v[208:209], v[208:209], v[154:155] op_sel:[0,1] op_sel_hi:[1,1]
	v_pk_fma_f32 v[208:209], v[172:173], v[208:209], v[176:177]
	v_pk_mul_f32 v[208:209], v[208:209], s[26:27] op_sel_hi:[1,0]
	v_pk_fma_f32 v[12:13], v[12:13], v[168:169], v[208:209]
	global_store_dwordx4 v[184:185], v[10:13], off offset:64
	global_load_dwordx4 v[166:169], v[178:179], off offset:512
	global_load_dwordx4 v[170:173], v[180:181], off offset:512
	global_load_dwordx4 v[174:177], v[210:211], off offset:512
	v_mov_b64_e32 v[182:183], v[156:157]
	s_mov_b64 s[24:25], 0x20000
	v_mov_b64_e32 v[184:185], v[182:183]
	global_load_dwordx4 v[194:197], v[182:183], off offset:512
	v_lshl_add_u64 v[182:183], v[182:183], 0, s[24:25]
	global_load_dwordx4 v[198:201], v[182:183], off offset:512
	v_lshl_add_u64 v[182:183], v[182:183], 0, s[24:25]
	global_load_dwordx4 v[202:205], v[182:183], off offset:512
	v_lshl_add_u64 v[182:183], v[182:183], 0, s[24:25]
	global_load_dwordx4 v[206:209], v[182:183], off offset:512
	s_waitcnt vmcnt(0)
;     __device__ __forceinline__ void operator()(const f32x4 (&acc)[2][2][4][2], const Unit& u, int wr, int wc, int fr, int fq) const {
;     ...
;             for (int m = 0; m < 4; ++m) { const size_t off = (size_t)(row0 + ai * HALF + m * 16) * ldc + col0;
; #pragma unroll
;                 for (int bj = 0; bj < 2; ++bj)
; #pragma unroll
;                     for (int n = 0; n < 2; ++n) { const f32x4 xr = *(const f32x4*)(xres + off + bj * HALF + n * 16);
;                         *(f32x4*)(z + off + bj * HALF + n * 16) = xr * alpha + gv[bj][n] * acc[ai][bj][m][n]; }
;                 if (m == 3) asm volatile("" ::: "memory"); }
; __device__ __forceinline__ void phase_ln(const float* z, float* xo, const float* __restrict__ g, const float* __restrict__ b, const float* __restrict__ sc, const float* __restrict__ sh, bf16_t* __restrict__ u) {
;     ...
;                 const f32x4 o = (v[k][j] - mean[k]) * rstd[k] * gg + bb;
	v_pk_add_f32 v[166:167], v[166:167], 1.0 op_sel_hi:[1,0]
	v_pk_add_f32 v[168:169], v[168:169], 1.0 op_sel_hi:[1,0]
	v_pk_fma_f32 v[194:195], v[140:141], s[26:27], v[194:195] op_sel:[0,1,0] op_sel_hi:[0,1,1]
	v_pk_mul_f32 v[194:195], v[194:195], v[140:141] op_sel:[0,1] op_sel_hi:[1,1]
	v_pk_fma_f32 v[194:195], v[170:171], v[194:195], v[174:175]
	v_pk_mul_f32 v[194:195], v[194:195], s[26:27] op_sel_hi:[1,0]
	v_pk_fma_f32 v[118:119], v[118:119], v[166:167], v[194:195]
	v_pk_fma_f32 v[196:197], v[140:141], s[26:27], v[196:197] op_sel:[0,1,0] op_sel_hi:[0,1,1]
	v_pk_mul_f32 v[196:197], v[196:197], v[140:141] op_sel:[0,1] op_sel_hi:[1,1]
	v_pk_fma_f32 v[196:197], v[172:173], v[196:197], v[176:177]
	v_pk_mul_f32 v[196:197], v[196:197], s[26:27] op_sel_hi:[1,0]
	v_pk_fma_f32 v[120:121], v[120:121], v[168:169], v[196:197]
	global_store_dwordx4 v[184:185], v[118:121], off offset:512
	v_lshl_add_u64 v[184:185], v[184:185], 0, s[24:25]
	v_pk_fma_f32 v[198:199], v[142:143], s[26:27], v[198:199] op_sel:[0,1,0] op_sel_hi:[0,1,1]
	v_pk_mul_f32 v[198:199], v[198:199], v[142:143] op_sel:[0,1] op_sel_hi:[1,1]
	v_pk_fma_f32 v[198:199], v[170:171], v[198:199], v[174:175]
	v_pk_mul_f32 v[198:199], v[198:199], s[26:27] op_sel_hi:[1,0]
	v_pk_fma_f32 v[102:103], v[102:103], v[166:167], v[198:199]
	v_pk_fma_f32 v[200:201], v[142:143], s[26:27], v[200:201] op_sel:[0,1,0] op_sel_hi:[0,1,1]
	v_pk_mul_f32 v[200:201], v[200:201], v[142:143] op_sel:[0,1] op_sel_hi:[1,1]
	v_pk_fma_f32 v[200:201], v[172:173], v[200:201], v[176:177]
	v_pk_mul_f32 v[200:201], v[200:201], s[26:27] op_sel_hi:[1,0]
	v_pk_fma_f32 v[104:105], v[104:105], v[168:169], v[200:201]
	global_store_dwordx4 v[184:185], v[102:105], off offset:512
	v_lshl_add_u64 v[184:185], v[184:185], 0, s[24:25]
	v_pk_fma_f32 v[202:203], v[144:145], s[26:27], v[202:203] op_sel:[0,1,0] op_sel_hi:[0,1,1]
	v_pk_mul_f32 v[202:203], v[202:203], v[144:145] op_sel:[0,1] op_sel_hi:[1,1]
	v_pk_fma_f32 v[202:203], v[170:171], v[202:203], v[174:175]
	v_pk_mul_f32 v[202:203], v[202:203], s[26:27] op_sel_hi:[1,0]
	v_pk_fma_f32 v[86:87], v[86:87], v[166:167], v[202:203]
	v_pk_fma_f32 v[204:205], v[144:145], s[26:27], v[204:205] op_sel:[0,1,0] op_sel_hi:[0,1,1]
	v_pk_mul_f32 v[204:205], v[204:205], v[144:145] op_sel:[0,1] op_sel_hi:[1,1]
	v_pk_fma_f32 v[204:205], v[172:173], v[204:205], v[176:177]
	v_pk_mul_f32 v[204:205], v[204:205], s[26:27] op_sel_hi:[1,0]
	v_pk_fma_f32 v[88:89], v[88:89], v[168:169], v[204:205]
	global_store_dwordx4 v[184:185], v[86:89], off offset:512
	v_lshl_add_u64 v[184:185], v[184:185], 0, s[24:25]
	v_pk_fma_f32 v[206:207], v[146:147], s[26:27], v[206:207] op_sel:[0,1,0] op_sel_hi:[0,1,1]
	v_pk_mul_f32 v[206:207], v[206:207], v[146:147] op_sel:[0,1] op_sel_hi:[1,1]
	v_pk_fma_f32 v[206:207], v[170:171], v[206:207], v[174:175]
	v_pk_mul_f32 v[206:207], v[206:207], s[26:27] op_sel_hi:[1,0]
	v_pk_fma_f32 v[70:71], v[70:71], v[166:167], v[206:207]
	v_pk_fma_f32 v[208:209], v[146:147], s[26:27], v[208:209] op_sel:[0,1,0] op_sel_hi:[0,1,1]
	v_pk_mul_f32 v[208:209], v[208:209], v[146:147] op_sel:[0,1] op_sel_hi:[1,1]
	v_pk_fma_f32 v[208:209], v[172:173], v[208:209], v[176:177]
	v_pk_mul_f32 v[208:209], v[208:209], s[26:27] op_sel_hi:[1,0]
	v_pk_fma_f32 v[72:73], v[72:73], v[168:169], v[208:209]
	global_store_dwordx4 v[184:185], v[70:73], off offset:512
	s_mov_b64 s[24:25], 0x100000
	v_lshl_add_u64 v[182:183], v[156:157], 0, s[24:25]
	s_mov_b64 s[24:25], 0x20000
	v_mov_b64_e32 v[184:185], v[182:183]
	global_load_dwordx4 v[194:197], v[182:183], off offset:512
	v_lshl_add_u64 v[182:183], v[182:183], 0, s[24:25]
	global_load_dwordx4 v[198:201], v[182:183], off offset:512
	v_lshl_add_u64 v[182:183], v[182:183], 0, s[24:25]
	global_load_dwordx4 v[202:205], v[182:183], off offset:512
	v_lshl_add_u64 v[182:183], v[182:183], 0, s[24:25]
	global_load_dwordx4 v[206:209], v[182:183], off offset:512
	s_waitcnt vmcnt(0)
	v_pk_fma_f32 v[194:195], v[148:149], s[26:27], v[194:195] op_sel:[0,1,0] op_sel_hi:[0,1,1]
	v_pk_mul_f32 v[194:195], v[194:195], v[148:149] op_sel:[0,1] op_sel_hi:[1,1]
	v_pk_fma_f32 v[194:195], v[170:171], v[194:195], v[174:175]
	v_pk_mul_f32 v[194:195], v[194:195], s[26:27] op_sel_hi:[1,0]
	v_pk_fma_f32 v[54:55], v[54:55], v[166:167], v[194:195]
	v_pk_fma_f32 v[196:197], v[148:149], s[26:27], v[196:197] op_sel:[0,1,0] op_sel_hi:[0,1,1]
	v_pk_mul_f32 v[196:197], v[196:197], v[148:149] op_sel:[0,1] op_sel_hi:[1,1]
	v_pk_fma_f32 v[196:197], v[172:173], v[196:197], v[176:177]
	v_pk_mul_f32 v[196:197], v[196:197], s[26:27] op_sel_hi:[1,0]
	v_pk_fma_f32 v[56:57], v[56:57], v[168:169], v[196:197]
	global_store_dwordx4 v[184:185], v[54:57], off offset:512
	v_lshl_add_u64 v[184:185], v[184:185], 0, s[24:25]
	v_pk_fma_f32 v[198:199], v[150:151], s[26:27], v[198:199] op_sel:[0,1,0] op_sel_hi:[0,1,1]
	v_pk_mul_f32 v[198:199], v[198:199], v[150:151] op_sel:[0,1] op_sel_hi:[1,1]
	v_pk_fma_f32 v[198:199], v[170:171], v[198:199], v[174:175]
	v_pk_mul_f32 v[198:199], v[198:199], s[26:27] op_sel_hi:[1,0]
	v_pk_fma_f32 v[38:39], v[38:39], v[166:167], v[198:199]
	v_pk_fma_f32 v[200:201], v[150:151], s[26:27], v[200:201] op_sel:[0,1,0] op_sel_hi:[0,1,1]
	v_pk_mul_f32 v[200:201], v[200:201], v[150:151] op_sel:[0,1] op_sel_hi:[1,1]
	v_pk_fma_f32 v[200:201], v[172:173], v[200:201], v[176:177]
	v_pk_mul_f32 v[200:201], v[200:201], s[26:27] op_sel_hi:[1,0]
	v_pk_fma_f32 v[40:41], v[40:41], v[168:169], v[200:201]
	global_store_dwordx4 v[184:185], v[38:41], off offset:512
	v_lshl_add_u64 v[184:185], v[184:185], 0, s[24:25]
	v_pk_fma_f32 v[202:203], v[152:153], s[26:27], v[202:203] op_sel:[0,1,0] op_sel_hi:[0,1,1]
;     __device__ __forceinline__ void operator()(const f32x4 (&acc)[2][2][4][2], const Unit& u, int wr, int wc, int fr, int fq) const {
;     ...
;             for (int m = 0; m < 4; ++m) { const size_t off = (size_t)(row0 + ai * HALF + m * 16) * ldc + col0;
; #pragma unroll
;                 for (int bj = 0; bj < 2; ++bj)
; #pragma unroll
;                     for (int n = 0; n < 2; ++n) { const f32x4 xr = *(const f32x4*)(xres + off + bj * HALF + n * 16);
;                         *(f32x4*)(z + off + bj * HALF + n * 16) = xr * alpha + gv[bj][n] * acc[ai][bj][m][n]; }
;                 if (m == 3) asm volatile("" ::: "memory"); }
; __device__ __forceinline__ void phase_ln(const float* z, float* xo, const float* __restrict__ g, const float* __restrict__ b, const float* __restrict__ sc, const float* __restrict__ sh, bf16_t* __restrict__ u) {
;     ...
;                 const f32x4 o = (v[k][j] - mean[k]) * rstd[k] * gg + bb;
	v_pk_mul_f32 v[202:203], v[202:203], v[152:153] op_sel:[0,1] op_sel_hi:[1,1]
	v_pk_fma_f32 v[202:203], v[170:171], v[202:203], v[174:175]
	v_pk_mul_f32 v[202:203], v[202:203], s[26:27] op_sel_hi:[1,0]
	v_pk_fma_f32 v[22:23], v[22:23], v[166:167], v[202:203]
	v_pk_fma_f32 v[204:205], v[152:153], s[26:27], v[204:205] op_sel:[0,1,0] op_sel_hi:[0,1,1]
	v_pk_mul_f32 v[204:205], v[204:205], v[152:153] op_sel:[0,1] op_sel_hi:[1,1]
	v_pk_fma_f32 v[204:205], v[172:173], v[204:205], v[176:177]
	v_pk_mul_f32 v[204:205], v[204:205], s[26:27] op_sel_hi:[1,0]
	v_pk_fma_f32 v[24:25], v[24:25], v[168:169], v[204:205]
	global_store_dwordx4 v[184:185], v[22:25], off offset:512
	v_lshl_add_u64 v[184:185], v[184:185], 0, s[24:25]
	v_pk_fma_f32 v[206:207], v[154:155], s[26:27], v[206:207] op_sel:[0,1,0] op_sel_hi:[0,1,1]
	v_pk_mul_f32 v[206:207], v[206:207], v[154:155] op_sel:[0,1] op_sel_hi:[1,1]
	v_pk_fma_f32 v[206:207], v[170:171], v[206:207], v[174:175]
	v_pk_mul_f32 v[206:207], v[206:207], s[26:27] op_sel_hi:[1,0]
	v_pk_fma_f32 v[6:7], v[6:7], v[166:167], v[206:207]
	v_pk_fma_f32 v[208:209], v[154:155], s[26:27], v[208:209] op_sel:[0,1,0] op_sel_hi:[0,1,1]
	v_pk_mul_f32 v[208:209], v[208:209], v[154:155] op_sel:[0,1] op_sel_hi:[1,1]
	v_pk_fma_f32 v[208:209], v[172:173], v[208:209], v[176:177]
	v_pk_mul_f32 v[208:209], v[208:209], s[26:27] op_sel_hi:[1,0]
	v_pk_fma_f32 v[8:9], v[8:9], v[168:169], v[208:209]
	global_store_dwordx4 v[184:185], v[6:9], off offset:512
	global_load_dwordx4 v[166:169], v[178:179], off offset:576
	global_load_dwordx4 v[170:173], v[180:181], off offset:576
	global_load_dwordx4 v[174:177], v[210:211], off offset:576
	v_mov_b64_e32 v[182:183], v[156:157]
	s_mov_b64 s[24:25], 0x20000
	v_mov_b64_e32 v[184:185], v[182:183]
	global_load_dwordx4 v[194:197], v[182:183], off offset:576
	v_lshl_add_u64 v[182:183], v[182:183], 0, s[24:25]
	global_load_dwordx4 v[198:201], v[182:183], off offset:576
	v_lshl_add_u64 v[182:183], v[182:183], 0, s[24:25]
	global_load_dwordx4 v[202:205], v[182:183], off offset:576
	v_lshl_add_u64 v[182:183], v[182:183], 0, s[24:25]
	global_load_dwordx4 v[206:209], v[182:183], off offset:576
	s_waitcnt vmcnt(0)
	v_pk_add_f32 v[166:167], v[166:167], 1.0 op_sel_hi:[1,0]
	v_pk_add_f32 v[168:169], v[168:169], 1.0 op_sel_hi:[1,0]
	v_pk_fma_f32 v[194:195], v[140:141], s[26:27], v[194:195] op_sel:[0,1,0] op_sel_hi:[0,1,1]
	v_pk_mul_f32 v[194:195], v[194:195], v[140:141] op_sel:[0,1] op_sel_hi:[1,1]
	v_pk_fma_f32 v[194:195], v[170:171], v[194:195], v[174:175]
	v_pk_mul_f32 v[194:195], v[194:195], s[26:27] op_sel_hi:[1,0]
	v_pk_fma_f32 v[114:115], v[114:115], v[166:167], v[194:195]
	v_pk_fma_f32 v[196:197], v[140:141], s[26:27], v[196:197] op_sel:[0,1,0] op_sel_hi:[0,1,1]
	v_pk_mul_f32 v[196:197], v[196:197], v[140:141] op_sel:[0,1] op_sel_hi:[1,1]
	v_pk_fma_f32 v[196:197], v[172:173], v[196:197], v[176:177]
	v_pk_mul_f32 v[196:197], v[196:197], s[26:27] op_sel_hi:[1,0]
	v_pk_fma_f32 v[116:117], v[116:117], v[168:169], v[196:197]
	global_store_dwordx4 v[184:185], v[114:117], off offset:576
	v_lshl_add_u64 v[184:185], v[184:185], 0, s[24:25]
	v_pk_fma_f32 v[198:199], v[142:143], s[26:27], v[198:199] op_sel:[0,1,0] op_sel_hi:[0,1,1]
	v_pk_mul_f32 v[198:199], v[198:199], v[142:143] op_sel:[0,1] op_sel_hi:[1,1]
	v_pk_fma_f32 v[198:199], v[170:171], v[198:199], v[174:175]
	v_pk_mul_f32 v[198:199], v[198:199], s[26:27] op_sel_hi:[1,0]
	v_pk_fma_f32 v[98:99], v[98:99], v[166:167], v[198:199]
	v_pk_fma_f32 v[200:201], v[142:143], s[26:27], v[200:201] op_sel:[0,1,0] op_sel_hi:[0,1,1]
	v_pk_mul_f32 v[200:201], v[200:201], v[142:143] op_sel:[0,1] op_sel_hi:[1,1]
	v_pk_fma_f32 v[200:201], v[172:173], v[200:201], v[176:177]
	v_pk_mul_f32 v[200:201], v[200:201], s[26:27] op_sel_hi:[1,0]
	v_pk_fma_f32 v[100:101], v[100:101], v[168:169], v[200:201]
	global_store_dwordx4 v[184:185], v[98:101], off offset:576
	v_lshl_add_u64 v[184:185], v[184:185], 0, s[24:25]
	v_pk_fma_f32 v[202:203], v[144:145], s[26:27], v[202:203] op_sel:[0,1,0] op_sel_hi:[0,1,1]
	v_pk_mul_f32 v[202:203], v[202:203], v[144:145] op_sel:[0,1] op_sel_hi:[1,1]
	v_pk_fma_f32 v[202:203], v[170:171], v[202:203], v[174:175]
	v_pk_mul_f32 v[202:203], v[202:203], s[26:27] op_sel_hi:[1,0]
	v_pk_fma_f32 v[82:83], v[82:83], v[166:167], v[202:203]
	v_pk_fma_f32 v[204:205], v[144:145], s[26:27], v[204:205] op_sel:[0,1,0] op_sel_hi:[0,1,1]
	v_pk_mul_f32 v[204:205], v[204:205], v[144:145] op_sel:[0,1] op_sel_hi:[1,1]
	v_pk_fma_f32 v[204:205], v[172:173], v[204:205], v[176:177]
	v_pk_mul_f32 v[204:205], v[204:205], s[26:27] op_sel_hi:[1,0]
	v_pk_fma_f32 v[84:85], v[84:85], v[168:169], v[204:205]
	global_store_dwordx4 v[184:185], v[82:85], off offset:576
	v_lshl_add_u64 v[184:185], v[184:185], 0, s[24:25]
	v_pk_fma_f32 v[206:207], v[146:147], s[26:27], v[206:207] op_sel:[0,1,0] op_sel_hi:[0,1,1]
	v_pk_mul_f32 v[206:207], v[206:207], v[146:147] op_sel:[0,1] op_sel_hi:[1,1]
	v_pk_fma_f32 v[206:207], v[170:171], v[206:207], v[174:175]
	v_pk_mul_f32 v[206:207], v[206:207], s[26:27] op_sel_hi:[1,0]
	v_pk_fma_f32 v[66:67], v[66:67], v[166:167], v[206:207]
	v_pk_fma_f32 v[208:209], v[146:147], s[26:27], v[208:209] op_sel:[0,1,0] op_sel_hi:[0,1,1]
	v_pk_mul_f32 v[208:209], v[208:209], v[146:147] op_sel:[0,1] op_sel_hi:[1,1]
	v_pk_fma_f32 v[208:209], v[172:173], v[208:209], v[176:177]
	v_pk_mul_f32 v[208:209], v[208:209], s[26:27] op_sel_hi:[1,0]
	v_pk_fma_f32 v[68:69], v[68:69], v[168:169], v[208:209]
	global_store_dwordx4 v[184:185], v[66:69], off offset:576
	s_mov_b64 s[24:25], 0x100000
	v_lshl_add_u64 v[182:183], v[156:157], 0, s[24:25]
	s_mov_b64 s[24:25], 0x20000
	v_mov_b64_e32 v[184:185], v[182:183]
	global_load_dwordx4 v[194:197], v[182:183], off offset:576
	v_lshl_add_u64 v[182:183], v[182:183], 0, s[24:25]
	global_load_dwordx4 v[198:201], v[182:183], off offset:576
	v_lshl_add_u64 v[182:183], v[182:183], 0, s[24:25]
	global_load_dwordx4 v[202:205], v[182:183], off offset:576
	v_lshl_add_u64 v[182:183], v[182:183], 0, s[24:25]
	global_load_dwordx4 v[206:209], v[182:183], off offset:576
	s_waitcnt vmcnt(0)
;     __device__ __forceinline__ void operator()(const f32x4 (&acc)[2][2][4][2], const Unit& u, int wr, int wc, int fr, int fq) const {
;     ...
;             for (int m = 0; m < 4; ++m) { const size_t off = (size_t)(row0 + ai * HALF + m * 16) * ldc + col0;
; #pragma unroll
;                 for (int bj = 0; bj < 2; ++bj)
; #pragma unroll
;                     for (int n = 0; n < 2; ++n) { const f32x4 xr = *(const f32x4*)(xres + off + bj * HALF + n * 16);
;                         *(f32x4*)(z + off + bj * HALF + n * 16) = xr * alpha + gv[bj][n] * acc[ai][bj][m][n]; }
;                 if (m == 3) asm volatile("" ::: "memory"); }
; __device__ __forceinline__ void phase_ln(const float* z, float* xo, const float* __restrict__ g, const float* __restrict__ b, const float* __restrict__ sc, const float* __restrict__ sh, bf16_t* __restrict__ u) {
;     ...
;                 const f32x4 o = (v[k][j] - mean[k]) * rstd[k] * gg + bb;
	v_pk_fma_f32 v[194:195], v[148:149], s[26:27], v[194:195] op_sel:[0,1,0] op_sel_hi:[0,1,1]
	v_pk_mul_f32 v[194:195], v[194:195], v[148:149] op_sel:[0,1] op_sel_hi:[1,1]
	v_pk_fma_f32 v[194:195], v[170:171], v[194:195], v[174:175]
	v_pk_mul_f32 v[194:195], v[194:195], s[26:27] op_sel_hi:[1,0]
	v_pk_fma_f32 v[50:51], v[50:51], v[166:167], v[194:195]
	v_pk_fma_f32 v[196:197], v[148:149], s[26:27], v[196:197] op_sel:[0,1,0] op_sel_hi:[0,1,1]
	v_pk_mul_f32 v[196:197], v[196:197], v[148:149] op_sel:[0,1] op_sel_hi:[1,1]
	v_pk_fma_f32 v[196:197], v[172:173], v[196:197], v[176:177]
	v_pk_mul_f32 v[196:197], v[196:197], s[26:27] op_sel_hi:[1,0]
	v_pk_fma_f32 v[52:53], v[52:53], v[168:169], v[196:197]
	global_store_dwordx4 v[184:185], v[50:53], off offset:576
	v_lshl_add_u64 v[184:185], v[184:185], 0, s[24:25]
	v_pk_fma_f32 v[198:199], v[150:151], s[26:27], v[198:199] op_sel:[0,1,0] op_sel_hi:[0,1,1]
	v_pk_mul_f32 v[198:199], v[198:199], v[150:151] op_sel:[0,1] op_sel_hi:[1,1]
	v_pk_fma_f32 v[198:199], v[170:171], v[198:199], v[174:175]
	v_pk_mul_f32 v[198:199], v[198:199], s[26:27] op_sel_hi:[1,0]
	v_pk_fma_f32 v[34:35], v[34:35], v[166:167], v[198:199]
	v_pk_fma_f32 v[200:201], v[150:151], s[26:27], v[200:201] op_sel:[0,1,0] op_sel_hi:[0,1,1]
	v_pk_mul_f32 v[200:201], v[200:201], v[150:151] op_sel:[0,1] op_sel_hi:[1,1]
	v_pk_fma_f32 v[200:201], v[172:173], v[200:201], v[176:177]
	v_pk_mul_f32 v[200:201], v[200:201], s[26:27] op_sel_hi:[1,0]
	v_pk_fma_f32 v[36:37], v[36:37], v[168:169], v[200:201]
	global_store_dwordx4 v[184:185], v[34:37], off offset:576
	v_lshl_add_u64 v[184:185], v[184:185], 0, s[24:25]
	v_pk_fma_f32 v[202:203], v[152:153], s[26:27], v[202:203] op_sel:[0,1,0] op_sel_hi:[0,1,1]
	v_pk_mul_f32 v[202:203], v[202:203], v[152:153] op_sel:[0,1] op_sel_hi:[1,1]
	v_pk_fma_f32 v[202:203], v[170:171], v[202:203], v[174:175]
	v_pk_mul_f32 v[202:203], v[202:203], s[26:27] op_sel_hi:[1,0]
	v_pk_fma_f32 v[18:19], v[18:19], v[166:167], v[202:203]
	v_pk_fma_f32 v[204:205], v[152:153], s[26:27], v[204:205] op_sel:[0,1,0] op_sel_hi:[0,1,1]
	v_pk_mul_f32 v[204:205], v[204:205], v[152:153] op_sel:[0,1] op_sel_hi:[1,1]
	v_pk_fma_f32 v[204:205], v[172:173], v[204:205], v[176:177]
	v_pk_mul_f32 v[204:205], v[204:205], s[26:27] op_sel_hi:[1,0]
	v_pk_fma_f32 v[20:21], v[20:21], v[168:169], v[204:205]
	global_store_dwordx4 v[184:185], v[18:21], off offset:576
	v_lshl_add_u64 v[184:185], v[184:185], 0, s[24:25]
	v_pk_fma_f32 v[206:207], v[154:155], s[26:27], v[206:207] op_sel:[0,1,0] op_sel_hi:[0,1,1]
	v_pk_mul_f32 v[206:207], v[206:207], v[154:155] op_sel:[0,1] op_sel_hi:[1,1]
	v_pk_fma_f32 v[206:207], v[170:171], v[206:207], v[174:175]
	v_pk_mul_f32 v[206:207], v[206:207], s[26:27] op_sel_hi:[1,0]
	v_pk_fma_f32 v[2:3], v[2:3], v[166:167], v[206:207]
	v_pk_fma_f32 v[208:209], v[154:155], s[26:27], v[208:209] op_sel:[0,1,0] op_sel_hi:[0,1,1]
	v_pk_mul_f32 v[208:209], v[208:209], v[154:155] op_sel:[0,1] op_sel_hi:[1,1]
	v_pk_fma_f32 v[208:209], v[172:173], v[208:209], v[176:177]
	v_pk_mul_f32 v[208:209], v[208:209], s[26:27] op_sel_hi:[1,0]
	v_pk_fma_f32 v[4:5], v[4:5], v[168:169], v[208:209]
	global_store_dwordx4 v[184:185], v[2:5], off offset:576
	s_and_b64 vcc, exec, s[4:5]
	s_mov_b64 s[24:25], -1
	s_cbranch_vccnz .LBB0_1255
	s_andn2_b64 vcc, exec, s[12:13]
	s_cbranch_vccnz .LBB0_1254
	s_barrier
	s_branch .LBB0_1254
